# XCD-hierarchical grid barrier (one L2 write-back per XCD, per-XCC counters with census) replaces flat 256-way counter barrier; attention gate loads hoisted; role-split k-loops
# speedup vs baseline: 1.0858x; 1.0391x over previous
; __global__ void __launch_bounds__(NTHR) mega_fwd(Params p) {
;     extern __shared__ __attribute__((aligned(16))) char lds[];
;     cg::grid_group grid = cg::this_grid();
;     const int nb = gridDim.x, bid = blockIdx.x;
;     if (bid == 0 && threadIdx.x < 256) __hip_atomic_store(WS_PTR(unsigned, OFF_HL) + threadIdx.x, 0u, __ATOMIC_RELAXED, __HIP_MEMORY_SCOPE_AGENT);
;     prep_phase(p, lds);
;     unsigned* bar = WS_PTR(unsigned, OFF_HL);
_Z8mega_fwd6Params:
	s_load_dwordx16 s[4:19], s[0:1], 0x80
	v_and_b32_e32 v212, 0x3ff, v0
	s_mov_b32 s50, s2
	v_mov_b32_e32 v245, 0
	s_waitcnt lgkmcnt(0)
	v_writelane_b32 v244, s4, 0
	s_nop 1
	v_writelane_b32 v244, s5, 1
	v_writelane_b32 v244, s6, 2
	v_writelane_b32 v244, s7, 3
	v_writelane_b32 v244, s8, 4
	v_writelane_b32 v244, s9, 5
	v_writelane_b32 v244, s10, 6
	v_writelane_b32 v244, s11, 7
	v_writelane_b32 v244, s12, 8
	v_writelane_b32 v244, s13, 9
	v_writelane_b32 v244, s14, 10
	v_writelane_b32 v244, s15, 11
	v_writelane_b32 v244, s16, 12
	v_writelane_b32 v244, s17, 13
	v_writelane_b32 v244, s18, 14
	v_writelane_b32 v244, s19, 15
	s_add_u32 s4, s0, 0xc0
	s_addc_u32 s5, s1, 0
	v_writelane_b32 v244, s4, 16
	s_cmp_eq_u32 s2, 0
	s_cselect_b64 s[2:3], -1, 0
	v_writelane_b32 v244, s5, 17
	s_load_dword s4, s[0:1], 0xc0
	s_waitcnt lgkmcnt(0)
	v_writelane_b32 v244, s4, 18
	s_nop 1
	v_writelane_b32 v244, s5, 19
	s_movk_i32 s4, 0x100
	v_cmp_gt_u32_e32 vcc, s4, v212
	s_and_b64 s[4:5], s[2:3], vcc
	s_and_saveexec_b64 s[2:3], s[4:5]
	s_cbranch_execz .LBB0_2
	s_load_dwordx16 s[4:19], s[0:1], 0x80
	v_lshlrev_b32_e32 v2, 2, v212
	v_mov_b32_e32 v3, 0
	s_waitcnt lgkmcnt(0)
	v_lshl_add_u64 v[4:5], s[18:19], 0, v[2:3]
	v_add_co_u32_e32 v4, vcc, 0x17000000, v4
	s_nop 1
	v_addc_co_u32_e32 v5, vcc, 0, v5, vcc
	global_store_dword v[4:5], v3, off sc1

; template <int N> DI void wait_vm() { asm volatile("s_waitcnt vmcnt(%0)" ::"n"(N) : "memory"); }
; DI void fast_grid_barrier(unsigned* ctr, unsigned target) {
;     wait_vm<0>();
;     __syncthreads();
;     if (threadIdx.x == 0) {
;         __builtin_amdgcn_fence(__ATOMIC_RELEASE, "agent");
;         __hip_atomic_fetch_add(ctr, 1u, __ATOMIC_RELAXED, __HIP_MEMORY_SCOPE_AGENT);
;         while (__hip_atomic_load(ctr, __ATOMIC_RELAXED, __HIP_MEMORY_SCOPE_AGENT) < target) __builtin_amdgcn_s_sleep(6);
;         __builtin_amdgcn_fence(__ATOMIC_ACQUIRE, "agent");
;     }
;     __syncthreads();
; }
.LBB0_62:
	s_cmp_lg_u32 s12, 0
	s_cbranch_scc0 .LBB0_70
	s_waitcnt vmcnt(0)
	s_barrier
	s_mov_b64 s[0:1], exec
	v_readlane_b32 s2, v243, 32
	v_readlane_b32 s3, v243, 33
	s_and_b64 s[2:3], s[0:1], s[2:3]
	s_mov_b64 exec, s[2:3]
	s_cbranch_execz .LBB0_69
	v_readlane_b32 s10, v244, 42
	v_readlane_b32 s11, v244, 43
	s_getreg_b32 s6, hwreg(HW_REG_XCC_ID, 0, 4)
	s_lshl_b32 s6, s6, 2
	v_mov_b32_e32 v2, s6
	v_mov_b32_e32 v3, 1
	v_readlane_b32 s3, v245, 0
	s_nop 3
	s_cmp_lg_u32 s3, 0
	s_cbranch_scc1 .Lxb_arrive
	v_readlane_b32 s2, v244, 18
.Lxb_census:
	global_load_dwordx4 v[4:7], v1, s[10:11] offset:640 sc1
	global_load_dwordx4 v[8:11], v1, s[10:11] offset:656 sc1
	global_load_dwordx4 v[12:15], v1, s[10:11] offset:672 sc1
	global_load_dwordx4 v[16:19], v1, s[10:11] offset:688 sc1
	global_load_dword v20, v2, s[10:11] offset:640 sc1
	s_waitcnt vmcnt(0)
	v_add3_u32 v21, v4, v5, v6
	v_add3_u32 v21, v21, v7, v8
	v_add3_u32 v21, v21, v9, v10
	v_add3_u32 v21, v21, v11, v12
	v_add3_u32 v21, v21, v13, v14
	v_add3_u32 v21, v21, v15, v16
	v_add3_u32 v21, v21, v17, v18
	v_add_u32_e32 v21, v21, v19
	v_cmp_ne_u32_e32 vcc, s2, v21
	s_cbranch_vccz .Lxb_census_ok
	s_sleep 2
	s_branch .Lxb_census
.Lxb_census_ok:
	v_mov_b32_e32 v22, 0
	v_cmp_ne_u32_e32 vcc, 0, v4
	s_nop 1
	v_addc_co_u32_e32 v22, vcc, 0, v22, vcc
	v_cmp_ne_u32_e32 vcc, 0, v5
	s_nop 1
	v_addc_co_u32_e32 v22, vcc, 0, v22, vcc
	v_cmp_ne_u32_e32 vcc, 0, v6
	s_nop 1
	v_addc_co_u32_e32 v22, vcc, 0, v22, vcc
	v_cmp_ne_u32_e32 vcc, 0, v7
	s_nop 1
	v_addc_co_u32_e32 v22, vcc, 0, v22, vcc
	v_cmp_ne_u32_e32 vcc, 0, v8
	s_nop 1
	v_addc_co_u32_e32 v22, vcc, 0, v22, vcc
	v_cmp_ne_u32_e32 vcc, 0, v9
	s_nop 1
	v_addc_co_u32_e32 v22, vcc, 0, v22, vcc
	v_cmp_ne_u32_e32 vcc, 0, v10
	s_nop 1
	v_addc_co_u32_e32 v22, vcc, 0, v22, vcc
	v_cmp_ne_u32_e32 vcc, 0, v11
	s_nop 1
	v_addc_co_u32_e32 v22, vcc, 0, v22, vcc
	v_cmp_ne_u32_e32 vcc, 0, v12
	s_nop 1
	v_addc_co_u32_e32 v22, vcc, 0, v22, vcc
	v_cmp_ne_u32_e32 vcc, 0, v13
	s_nop 1
	v_addc_co_u32_e32 v22, vcc, 0, v22, vcc
	v_cmp_ne_u32_e32 vcc, 0, v14
	s_nop 1
	v_addc_co_u32_e32 v22, vcc, 0, v22, vcc
	v_cmp_ne_u32_e32 vcc, 0, v15
	s_nop 1
	v_addc_co_u32_e32 v22, vcc, 0, v22, vcc
	v_cmp_ne_u32_e32 vcc, 0, v16
	s_nop 1
	v_addc_co_u32_e32 v22, vcc, 0, v22, vcc
	v_cmp_ne_u32_e32 vcc, 0, v17
	s_nop 1
	v_addc_co_u32_e32 v22, vcc, 0, v22, vcc
	v_cmp_ne_u32_e32 vcc, 0, v18
	s_nop 1
	v_addc_co_u32_e32 v22, vcc, 0, v22, vcc
	v_cmp_ne_u32_e32 vcc, 0, v19
	s_nop 1
	v_addc_co_u32_e32 v22, vcc, 0, v22, vcc
	v_readfirstlane_b32 s3, v20
	v_readfirstlane_b32 s7, v22
	s_nop 3
	v_writelane_b32 v245, s3, 0
	v_writelane_b32 v245, s7, 1
.Lxb_arrive:
	global_atomic_add v0, v2, v3, s[10:11] offset:704 sc0
	s_waitcnt vmcnt(0)
	v_readfirstlane_b32 s6, v0
	s_nop 3
	s_add_u32 s6, s6, 1
	s_mul_i32 s7, s12, s3
	s_cmp_eq_u32 s6, s7
	s_cbranch_scc0 .Lxb_follow
	buffer_wbl2 sc1
	s_waitcnt vmcnt(0)
	global_atomic_add v0, v1, v3, s[10:11] offset:832 sc0
	s_waitcnt vmcnt(0)
	v_readfirstlane_b32 s6, v0
	v_readlane_b32 s7, v245, 1
	s_nop 3
	s_add_u32 s6, s6, 1
	s_mul_i32 s7, s12, s7
	s_cmp_eq_u32 s6, s7
	s_cbranch_scc0 .Lxb_wait_top
	global_atomic_add v1, v3, s[10:11] offset:836
	s_branch .Lxb_top_done
.Lxb_wait_top:
	s_sleep 1
	global_load_dword v0, v1, s[10:11] offset:836 sc1
	s_waitcnt vmcnt(0)
	v_cmp_gt_u32_e32 vcc, s12, v0
	s_cbranch_vccnz .Lxb_wait_top
.Lxb_top_done:
	buffer_inv sc1
	global_atomic_add v2, v3, s[10:11] offset:768
	s_waitcnt vmcnt(0)
	s_branch .LBB0_69
.Lxb_follow:
	s_sleep 1
	global_load_dword v0, v2, s[10:11] offset:768 sc1
	s_waitcnt vmcnt(0)
	v_cmp_gt_u32_e32 vcc, s12, v0
	s_cbranch_vccnz .Lxb_follow
	buffer_inv sc1
	s_waitcnt vmcnt(0)

; __global__ void __launch_bounds__(NTHR) mega_fwd(Params p) {
;     ...
;     for (int ph = 0; ph < 4; ++ph) {
;         if (ph == 0) grid.sync(); else fast_grid_barrier(bar, (unsigned)ph * (unsigned)nb);
;         const int l = ph >> 1;
;         if ((ph & 1) == 0) {
;             const int nkv = (l == 0) ? 256 : 0, nunits = 256 + nkv + 1024 + 256 + 256;
;             for (int u = bid; u < nunits; u += nb) {
;                 int v = u;
;                 if (v < 256) { unit_B1(p, lds, l, v); continue; }
;                 v -= 256;
;                 if (v < nkv) { unit_KV(p, lds, v >> 7, (v >> 2) & 31, v & 3); continue; }
;                 v -= nkv;
;                 if (v < 1024) { unit_A(p, lds, l, v & 255, v >> 8); continue; }
;                 v -= 1024;
;                 const int s = v & 255, xcd = s & 7, i = s >> 3;
;                 if (v < 256) unit_X(p, lds, l, xcd * 32 + i);
;                 else unit_S5(p, lds, l, xcd * 2 + (i >> 4), i & 15);
.LBB0_81:
	s_or_b64 exec, exec, s[0:1]
	s_barrier
	s_mov_b64 s[0:1], exec
	v_readlane_b32 s2, v243, 32
	v_readlane_b32 s3, v243, 33
	s_nop 3
	s_and_b64 s[2:3], s[0:1], s[2:3]
	s_mov_b64 exec, s[2:3]
	s_cbranch_execz .Lxb_posted
	v_readlane_b32 s10, v244, 42
	v_readlane_b32 s11, v244, 43
	s_getreg_b32 s6, hwreg(HW_REG_XCC_ID, 0, 4)
	s_lshl_b32 s6, s6, 2
	v_mov_b32_e32 v2, s6
	v_mov_b32_e32 v3, 1
	s_nop 4
	global_atomic_add v2, v3, s[10:11] offset:640
.Lxb_posted:
	s_or_b64 exec, exec, s[0:1]
.LBB0_82:
	s_lshr_b32 s26, s12, 1
	s_bitcmp0_b32 s12, 0
	s_mov_b64 s[0:1], -1
	s_cbranch_scc1 .LBB0_658
	v_writelane_b32 v243, s26, 36
	v_readlane_b32 s0, v244, 44
	v_readlane_b32 s1, v244, 45
	v_writelane_b32 v243, s27, 37
	v_writelane_b32 v243, s12, 38
	s_andn2_b64 vcc, exec, s[0:1]
	s_nop 0
	v_writelane_b32 v243, s13, 39
	s_cbranch_vccnz .LBB0_657
	v_readlane_b32 s8, v243, 38
	v_readlane_b32 s9, v243, 39
	v_readlane_b32 s34, v243, 36
	s_lshl_b64 s[6:7], s[8:9], 16
	s_lshl_b32 s40, s34, 8
	s_and_b32 s6, s6, 0xfffe0000
	s_lshl_b64 s[0:1], s[40:41], 2
	v_readlane_b32 s16, v244, 0
	v_readlane_b32 s17, v244, 1
	s_add_u32 s2, s16, s0
	s_addc_u32 s3, s17, s1
	s_cmp_gt_u32 s8, 1
	s_cselect_b64 s[10:11], -1, 0
	s_lshl_b32 s40, s34, 10
	v_readlane_b32 s26, v244, 10
	s_lshl_b64 s[0:1], s[40:41], 2
	v_readlane_b32 s27, v244, 11
	s_add_u32 s12, s26, s0
	v_readlane_b32 s24, v244, 8
	s_addc_u32 s13, s27, s1
	v_readlane_b32 s25, v244, 9
	s_add_u32 s14, s24, s0
	s_addc_u32 s15, s25, s1
	v_readlane_b32 s29, v244, 13
	s_cmp_lt_u32 s8, 2
	v_readlane_b32 s0, v244, 56
	v_readlane_b32 s28, v244, 12
	s_cselect_b32 s17, s0, s29
	v_readlane_b32 s0, v244, 55
	v_readlane_b32 s18, v244, 2
	s_cselect_b32 s16, s0, s28
	s_lshl_b32 s0, s34, 21
	v_readlane_b32 s8, v244, 50
	v_readlane_b32 s19, v244, 3
	v_readlane_b32 s22, v244, 6
	s_add_u32 s18, s8, s0
	v_readlane_b32 s9, v244, 51
	v_readlane_b32 s20, v244, 4
	s_addc_u32 s19, s9, 0
	v_readlane_b32 s22, v243, 22
	v_readlane_b32 s21, v244, 5
	s_add_u32 s20, s18, s22
	s_addc_u32 s21, s19, 0
	s_add_u32 s0, s18, s22
	s_addc_u32 s1, s19, 0
	s_add_u32 s24, s0, 0x1000
	s_addc_u32 s25, s1, 0
	v_readlane_b32 s35, v243, 37
	v_writelane_b32 v243, s24, 40
	s_mov_b32 s35, s41
	v_readlane_b32 s23, v244, 7
	v_writelane_b32 v243, s25, 41
	s_add_u32 s24, s0, 0x3000
	s_addc_u32 s25, s1, 0
	v_writelane_b32 v243, s24, 42
	v_readlane_b32 s30, v244, 14
	v_readlane_b32 s31, v244, 15
	v_writelane_b32 v243, s25, 43
	s_add_u32 s24, s0, 0x5000
	s_addc_u32 s25, s1, 0
	v_writelane_b32 v243, s24, 44
	s_nop 1
	v_writelane_b32 v243, s25, 45
	s_add_u32 s24, s0, 0x7000
	s_addc_u32 s25, s1, 0
	v_writelane_b32 v243, s24, 46
	s_nop 1
	v_writelane_b32 v243, s25, 47
	s_add_u32 s24, s0, 0x9000
	s_addc_u32 s25, s1, 0
	v_writelane_b32 v243, s24, 48
	s_nop 1
	v_writelane_b32 v243, s25, 49
	s_add_u32 s24, s0, 0xb000
	s_addc_u32 s25, s1, 0
	v_writelane_b32 v243, s24, 50
	s_nop 1
	v_writelane_b32 v243, s25, 51
	s_add_u32 s24, s0, 0xd000
	s_addc_u32 s25, s1, 0
	v_writelane_b32 v243, s24, 52
	s_add_u32 s0, s0, 0xf000
	s_addc_u32 s1, s1, 0
	v_writelane_b32 v243, s25, 53
	v_writelane_b32 v243, s0, 54
	s_nop 1
	v_writelane_b32 v243, s1, 55
	s_mov_b32 s0, s34
	v_writelane_b32 v243, s0, 36
	s_nop 1
	v_writelane_b32 v243, s1, 37
	s_lshl_b64 s[0:1], s[34:35], 21
	s_add_u32 s70, s8, s0
	s_addc_u32 s71, s9, s1
	s_add_u32 s8, s70, s22
	s_addc_u32 s9, s71, 0
	s_add_u32 s0, s8, 0x1000
	s_addc_u32 s1, s9, 0
	s_add_u32 s50, s8, 0x3000
	s_addc_u32 s51, s9, 0
	s_add_u32 s44, s8, 0x5000
	v_writelane_b32 v243, s0, 56
	s_addc_u32 s45, s9, 0
	v_readlane_b32 s34, v244, 36
	v_writelane_b32 v243, s1, 57
	s_add_u32 s0, s8, 0x7000
	s_addc_u32 s1, s9, 0
	s_add_u32 s22, s8, 0x9000
	s_addc_u32 s23, s9, 0
	s_add_u32 s24, s8, 0xb000
	s_addc_u32 s25, s9, 0
	s_add_u32 s26, s8, 0xd000
	s_addc_u32 s27, s9, 0
	s_add_u32 s8, s8, 0xf000
	s_addc_u32 s9, s9, 0
	s_add_u32 s30, s30, s6
	v_writelane_b32 v243, s8, 58
	s_addc_u32 s31, s31, s7
	v_readlane_b32 s35, v244, 37
	v_writelane_b32 v243, s9, 59
	s_branch .LBB0_86

; template <int N> DI void wait_vm() { asm volatile("s_waitcnt vmcnt(%0)" ::"n"(N) : "memory"); }
; DI void raw_barrier() { asm volatile("" ::: "memory"); __builtin_amdgcn_s_barrier(); asm volatile("" ::: "memory"); }
; DI void unit_X(const Params& p, char* lds, int l, int chunk) {
;     ...
;     auto issue_kv = [&](int h, int buf) {
;         const bf16_t* Kh = Kb + (size_t)h * 256 * 64;
;         const bf16_t* Vh = Vb + (size_t)h * 64 * 256;
;         char* kd = lds + buf * 65536;
;         char* vd = kd + 32768;
; #pragma unroll
;         for (int i = 0; i < 4; ++i) {
;             const int piece = wid + 8 * i;
;             {
;                 const int row = piece * 8 + (lane >> 3), lc = (lane & 7) ^ ((row >> 1) & 7);
;                 __builtin_amdgcn_global_load_lds((const unsigned*)(Kh + row * 64 + lc * 8), (unsigned*)(kd + piece * 1024 + lane * 16), 16, 0, 0);
;             }
;             {
;                 const int row = piece * 2 + (lane >> 5), lc = (lane & 31) ^ (row & 15);
;                 __builtin_amdgcn_global_load_lds((const unsigned*)(Vh + row * 256 + lc * 8), (unsigned*)(vd + piece * 1024 + lane * 16), 16, 0, 0);
;             }
;         }
;     };
;     issue_kv(0, 0);
;     const int tok = wid * 16 + l15;
; #pragma unroll
;     for (int h = 0; h < 4; ++h) {
;         wait_vm<0>();
;         raw_barrier();
;         if (h < 3) issue_kv(h + 1, (h + 1) & 1);
.LBB0_823:
	v_and_b32_e32 v37, 63, v137
	v_lshrrev_b32_e32 v40, 3, v37
	v_lshl_or_b32 v0, v35, 3, v40
	s_lshl_b32 s0, s0, 17
	v_readlane_b32 s1, v242, 19
	v_lshrrev_b32_e32 v38, 1, v0
	s_add_u32 s6, s1, s0
	v_readlane_b32 s1, v242, 20
	v_xor_b32_e32 v41, v38, v137
	v_lshlrev_b32_e32 v38, 6, v0
	s_addc_u32 s7, s1, 0
	v_readlane_b32 s1, v242, 21
	v_ashrrev_i32_e32 v39, 31, v38
	v_lshlrev_b32_e32 v0, 4, v41
	v_lshlrev_b32_e32 v41, 10, v35
	v_lshlrev_b32_e32 v42, 4, v37
	s_add_u32 s8, s1, s0
	v_readlane_b32 s0, v242, 22
	v_lshlrev_b64 v[82:83], 1, v[38:39]
	v_add3_u32 v132, 0, v41, v42
	s_addc_u32 s9, s0, 0
	v_lshl_add_u64 v[38:39], s[6:7], 0, v[82:83]
	v_and_b32_e32 v0, 0x70, v0
	v_readfirstlane_b32 s0, v132
	v_lshl_add_u64 v[38:39], v[38:39], 0, v[0:1]
	s_mov_b32 m0, s0
	v_lshrrev_b32_e32 v37, 5, v37
	s_waitcnt lgkmcnt(0)
	global_load_lds_dwordx4 v[38:39], off
	v_lshl_or_b32 v38, v35, 1, v37
	v_and_b32_e32 v43, 31, v137
	v_bitop3_b32 v44, v38, v43, 15 bitop3:0x6c
	v_lshlrev_b32_e32 v38, 8, v38
	v_ashrrev_i32_e32 v39, 31, v38
	v_lshlrev_b64 v[84:85], 1, v[38:39]
	v_add_u32_e32 v133, 0x8000, v132
	v_lshl_add_u64 v[38:39], s[8:9], 0, v[84:85]
	v_lshlrev_b32_e32 v86, 4, v44
	v_mov_b32_e32 v87, v1
	v_readfirstlane_b32 s0, v133
	v_lshl_add_u64 v[38:39], v[38:39], 0, v[86:87]
	s_mov_b32 m0, s0
	v_add_u32_e32 v44, 8, v35
	global_load_lds_dwordx4 v[38:39], off
	v_lshl_or_b32 v38, v44, 3, v40
	v_lshrrev_b32_e32 v39, 1, v38
	v_xor_b32_e32 v45, v39, v137
	v_lshlrev_b32_e32 v38, 6, v38
	v_lshlrev_b32_e32 v45, 4, v45
	v_ashrrev_i32_e32 v39, 31, v38
	v_and_b32_e32 v90, 0x70, v45
	v_lshlrev_b32_e32 v45, 10, v44
	v_lshlrev_b64 v[88:89], 1, v[38:39]
	v_add3_u32 v138, 0, v45, v42
	v_lshl_add_u64 v[38:39], s[6:7], 0, v[88:89]
	v_mov_b32_e32 v91, v1
	v_readfirstlane_b32 s0, v138
	v_lshl_add_u64 v[38:39], v[38:39], 0, v[90:91]
	s_mov_b32 m0, s0
	v_add_u32_e32 v139, 0x8000, v138
	global_load_lds_dwordx4 v[38:39], off
	v_lshl_or_b32 v38, v44, 1, v37
	v_bitop3_b32 v44, v38, v43, 15 bitop3:0x6c
	v_lshlrev_b32_e32 v38, 8, v38
	v_ashrrev_i32_e32 v39, 31, v38
	v_lshlrev_b64 v[92:93], 1, v[38:39]
	v_lshl_add_u64 v[38:39], s[8:9], 0, v[92:93]
	v_lshlrev_b32_e32 v94, 4, v44
	v_mov_b32_e32 v95, v1
	v_readfirstlane_b32 s0, v139
	v_lshl_add_u64 v[38:39], v[38:39], 0, v[94:95]
	s_mov_b32 m0, s0
	v_add_u32_e32 v44, 16, v35
	global_load_lds_dwordx4 v[38:39], off
	v_lshl_or_b32 v38, v44, 3, v40
	v_lshrrev_b32_e32 v39, 1, v38
	v_xor_b32_e32 v46, v39, v137
	v_lshlrev_b32_e32 v38, 6, v38
	v_lshlrev_b32_e32 v46, 4, v46
	v_ashrrev_i32_e32 v39, 31, v38
	v_and_b32_e32 v98, 0x70, v46
	v_lshlrev_b32_e32 v46, 10, v44
	v_lshlrev_b64 v[96:97], 1, v[38:39]
	v_add3_u32 v140, 0, v46, v42
	v_lshl_add_u64 v[38:39], s[6:7], 0, v[96:97]
	v_mov_b32_e32 v99, v1
	v_readfirstlane_b32 s0, v140
	v_lshl_add_u64 v[38:39], v[38:39], 0, v[98:99]
	s_mov_b32 m0, s0
	v_add_u32_e32 v141, 0x8000, v140
	global_load_lds_dwordx4 v[38:39], off
	v_lshl_or_b32 v38, v44, 1, v37
	v_bitop3_b32 v44, v38, v43, 15 bitop3:0x6c
	v_lshlrev_b32_e32 v38, 8, v38
	v_ashrrev_i32_e32 v39, 31, v38
	v_lshlrev_b64 v[100:101], 1, v[38:39]
	v_lshl_add_u64 v[38:39], s[8:9], 0, v[100:101]
	v_lshlrev_b32_e32 v102, 4, v44
	v_mov_b32_e32 v103, v1
	v_readfirstlane_b32 s0, v141
	v_lshl_add_u64 v[38:39], v[38:39], 0, v[102:103]
	s_mov_b32 m0, s0
	v_add_u32_e32 v35, 24, v35
	global_load_lds_dwordx4 v[38:39], off
	v_lshl_or_b32 v38, v35, 3, v40
	v_lshrrev_b32_e32 v39, 1, v38
	v_xor_b32_e32 v40, v39, v137
	v_lshlrev_b32_e32 v38, 6, v38
	v_lshlrev_b32_e32 v40, 4, v40
	v_ashrrev_i32_e32 v39, 31, v38
	v_and_b32_e32 v106, 0x70, v40
	v_lshlrev_b32_e32 v40, 10, v35
	v_lshlrev_b64 v[104:105], 1, v[38:39]
	v_add3_u32 v142, 0, v40, v42
	v_lshl_add_u64 v[38:39], s[6:7], 0, v[104:105]
	v_mov_b32_e32 v107, v1
	v_readfirstlane_b32 s0, v142
	v_lshl_add_u64 v[38:39], v[38:39], 0, v[106:107]
	s_mov_b32 m0, s0
	v_lshl_or_b32 v35, v35, 1, v37
	global_load_lds_dwordx4 v[38:39], off
	v_lshlrev_b32_e32 v38, 8, v35
	v_ashrrev_i32_e32 v39, 31, v38
	v_bitop3_b32 v37, v35, v43, 15 bitop3:0x6c
	v_lshlrev_b64 v[108:109], 1, v[38:39]
	v_add_u32_e32 v143, 0x8000, v142
	v_lshl_add_u64 v[38:39], s[8:9], 0, v[108:109]
	v_lshlrev_b32_e32 v110, 4, v37
	v_mov_b32_e32 v111, v1
	v_readfirstlane_b32 s0, v143
	v_lshl_add_u64 v[38:39], v[38:39], 0, v[110:111]
	s_mov_b32 m0, s0
	v_ashrrev_i32_e32 v35, 31, v34
	s_add_u32 s0, s6, 0x8000
	global_load_lds_dwordx4 v[38:39], off
	v_lshlrev_b64 v[38:39], 9, v[34:35]
	s_addc_u32 s1, s7, 0
	v_add3_u32 v118, s12, v41, v42
	v_lshl_add_u64 v[112:113], s[10:11], 0, v[38:39]
	s_add_u32 s14, s8, 0x8000
	v_readfirstlane_b32 s10, v118
	v_and_b32_e32 v153, 63, v34
	s_waitcnt vmcnt(0)
	s_addc_u32 s15, s9, 0
	v_lshl_add_u64 v[34:35], s[0:1], 0, v[82:83]
	s_mov_b32 m0, s10
	s_add_i32 s10, 0, 0x18000
	s_barrier
; DI f32x4 mfma16(bf16x8 a, bf16x8 b, f32x4 c) { return __builtin_amdgcn_mfma_f32_16x16x32_bf16(a, b, c, 0, 0, 0); }
; DI void unit_X(const Params& p, char* lds, int l, int chunk) {
;     ...
;         if (h < 3) issue_kv(h + 1, (h + 1) & 1);
;         const char* kd = lds + (h & 1) * 65536;
;         const char* vd = kd + 32768;
;         f32x4 s[16];
; #pragma unroll
;         for (int mt = 0; mt < 16; ++mt) s[mt] = (f32x4){0.f, 0.f, 0.f, 0.f};
; #pragma unroll
;         for (int ks = 0; ks < 2; ++ks) {
; #pragma unroll
;             for (int mt = 0; mt < 16; ++mt) {
;                 const int row = 16 * mt + l15;
;                 const bf16x8 ak = *(const bf16x8*)(kd + row * 128 + (((4 * ks + quad) ^ ((row >> 1) & 7)) << 4));
;                 s[mt] = mfma16(ak, bq[h][ks], s[mt]);
;             }
;         }
;         float mxv = -3.0e38f;
; #pragma unroll
;         for (int mt = 0; mt < 16; ++mt)
; #pragma unroll
;             for (int i = 0; i < 4; ++i) mxv = fmaxf(mxv, s[mt][i]);
;         mxv = fmaxf(mxv, __shfl_xor(mxv, 16));
	v_lshl_add_u64 v[34:35], v[34:35], 0, v[0:1]
	v_add3_u32 v119, s10, v41, v42
	global_load_lds_dwordx4 v[34:35], off
	v_lshl_add_u64 v[34:35], s[14:15], 0, v[84:85]
	v_readfirstlane_b32 s11, v119
	v_lshl_add_u64 v[34:35], v[34:35], 0, v[86:87]
	s_mov_b32 m0, s11
	v_add3_u32 v120, s12, v45, v42
	global_load_lds_dwordx4 v[34:35], off
	v_lshl_add_u64 v[34:35], s[0:1], 0, v[88:89]
	v_readfirstlane_b32 s11, v120
	v_lshl_add_u64 v[34:35], v[34:35], 0, v[90:91]
	s_mov_b32 m0, s11
	v_add3_u32 v121, s10, v45, v42
	global_load_lds_dwordx4 v[34:35], off
	v_lshl_add_u64 v[34:35], s[14:15], 0, v[92:93]
	v_readfirstlane_b32 s11, v121
	v_lshl_add_u64 v[34:35], v[34:35], 0, v[94:95]
	s_mov_b32 m0, s11
	v_add3_u32 v122, s12, v46, v42
	global_load_lds_dwordx4 v[34:35], off
	v_lshl_add_u64 v[34:35], s[0:1], 0, v[96:97]
	v_readfirstlane_b32 s11, v122
	v_lshl_add_u64 v[34:35], v[34:35], 0, v[98:99]
	s_mov_b32 m0, s11
	v_add3_u32 v123, s10, v46, v42
	global_load_lds_dwordx4 v[34:35], off
	v_lshl_add_u64 v[34:35], s[14:15], 0, v[100:101]
	v_readfirstlane_b32 s11, v123
	v_lshl_add_u64 v[34:35], v[34:35], 0, v[102:103]
	s_mov_b32 m0, s11
	v_add3_u32 v124, s12, v40, v42
	global_load_lds_dwordx4 v[34:35], off
	v_lshl_add_u64 v[34:35], s[0:1], 0, v[104:105]
	v_readfirstlane_b32 s0, v124
	v_lshl_add_u64 v[34:35], v[34:35], 0, v[106:107]
	s_mov_b32 m0, s0
	v_add3_u32 v125, s10, v40, v42
	global_load_lds_dwordx4 v[34:35], off
	v_lshl_add_u64 v[34:35], s[14:15], 0, v[108:109]
	v_readfirstlane_b32 s0, v125
	v_lshrrev_b32_e32 v37, 1, v137
	v_lshl_add_u64 v[34:35], v[34:35], 0, v[110:111]
	s_mov_b32 m0, s0
	v_lshlrev_b32_e32 v131, 7, v135
	global_load_lds_dwordx4 v[34:35], off
	v_bitop3_b32 v34, v136, v37, 7 bitop3:0x78
	v_bfe_u32 v66, v137, 1, 3
	v_lshlrev_b32_e32 v137, 4, v34
	v_add3_u32 v117, 0, v137, v131
	ds_read_b128 v[58:61], v117 offset:12288
	ds_read_b128 v[62:65], v117 offset:14336
	s_waitcnt lgkmcnt(0)
	v_mfma_f32_16x16x32_bf16 v[126:129], v[62:65], v[30:33], 0
	ds_read_b128 v[62:65], v117 offset:16384
	v_add_u32_e32 v152, s13, v36
	ds_read_b128 v[34:37], v117
	ds_read_b128 v[38:41], v117 offset:2048
	s_waitcnt lgkmcnt(0)
	v_mfma_f32_16x16x32_bf16 v[146:149], v[62:65], v[30:33], 0
	ds_read_b128 v[62:65], v117 offset:18432
	ds_read_b128 v[42:45], v117 offset:4096
	ds_read_b128 v[46:49], v117 offset:6144
	s_waitcnt lgkmcnt(0)
	v_mfma_f32_16x16x32_bf16 v[154:157], v[62:65], v[30:33], 0
	ds_read_b128 v[62:65], v117 offset:20480
	ds_read_b128 v[50:53], v117 offset:8192
	ds_read_b128 v[54:57], v117 offset:10240
	s_waitcnt lgkmcnt(0)
	v_mfma_f32_16x16x32_bf16 v[158:161], v[62:65], v[30:33], 0
	ds_read_b128 v[62:65], v117 offset:22528
	s_mov_b32 s13, 0xff61b1e6
	v_lshlrev_b32_e32 v130, 9, v135
	s_waitcnt lgkmcnt(0)
	v_mfma_f32_16x16x32_bf16 v[162:165], v[62:65], v[30:33], 0
	ds_read_b128 v[62:65], v117 offset:24576
	v_readfirstlane_b32 s11, v132
	s_mov_b32 m0, s11
	s_waitcnt lgkmcnt(0)
	v_mfma_f32_16x16x32_bf16 v[166:169], v[62:65], v[30:33], 0
	ds_read_b128 v[62:65], v117 offset:26624
	v_readfirstlane_b32 s11, v133
	s_waitcnt lgkmcnt(0)
	v_mfma_f32_16x16x32_bf16 v[170:173], v[62:65], v[30:33], 0
	ds_read_b128 v[62:65], v117 offset:28672
	s_waitcnt lgkmcnt(0)
	v_mfma_f32_16x16x32_bf16 v[174:177], v[62:65], v[30:33], 0
	ds_read_b128 v[62:65], v117 offset:30720
	v_mfma_f32_16x16x32_bf16 v[34:37], v[34:37], v[30:33], 0
	v_mfma_f32_16x16x32_bf16 v[38:41], v[38:41], v[30:33], 0
	v_mfma_f32_16x16x32_bf16 v[42:45], v[42:45], v[30:33], 0
	v_mfma_f32_16x16x32_bf16 v[46:49], v[46:49], v[30:33], 0
	v_mfma_f32_16x16x32_bf16 v[50:53], v[50:53], v[30:33], 0
	v_mfma_f32_16x16x32_bf16 v[54:57], v[54:57], v[30:33], 0
	v_mfma_f32_16x16x32_bf16 v[58:61], v[58:61], v[30:33], 0
	s_waitcnt lgkmcnt(0)
	v_mfma_f32_16x16x32_bf16 v[178:181], v[62:65], v[30:33], 0
	v_bitop3_b32 v30, v136, v66, 4 bitop3:0x36
	v_lshlrev_b32_e32 v144, 4, v30
	v_add3_u32 v116, 0, v144, v131
	ds_read_b128 v[30:33], v116
	s_waitcnt lgkmcnt(0)
	v_mfma_f32_16x16x32_bf16 v[182:185], v[30:33], v[26:29], v[34:37]
	ds_read_b128 v[30:33], v116 offset:2048
	s_nop 6
	v_max3_f32 v114, v182, s13, v183
	s_waitcnt lgkmcnt(0)
	v_mfma_f32_16x16x32_bf16 v[186:189], v[30:33], v[26:29], v[38:41]
	ds_read_b128 v[30:33], v116 offset:4096
	v_max3_f32 v114, v114, v184, v185
	s_nop 5
	v_max3_f32 v114, v114, v186, v187
	s_waitcnt lgkmcnt(0)
	v_mfma_f32_16x16x32_bf16 v[78:81], v[30:33], v[26:29], v[42:45]
	ds_read_b128 v[30:33], v116 offset:6144
	v_max3_f32 v114, v114, v188, v189
	s_nop 5
	v_max3_f32 v114, v114, v78, v79
	s_waitcnt lgkmcnt(0)
	v_mfma_f32_16x16x32_bf16 v[74:77], v[30:33], v[26:29], v[46:49]
	ds_read_b128 v[30:33], v116 offset:8192
	v_max3_f32 v114, v114, v80, v81
	s_nop 5
	v_max3_f32 v114, v114, v74, v75
	s_waitcnt lgkmcnt(0)
	v_mfma_f32_16x16x32_bf16 v[70:73], v[30:33], v[26:29], v[50:53]
	ds_read_b128 v[30:33], v116 offset:10240
	v_max3_f32 v114, v114, v76, v77
	s_nop 5
	v_max3_f32 v114, v114, v70, v71
	s_waitcnt lgkmcnt(0)
	v_mfma_f32_16x16x32_bf16 v[66:69], v[30:33], v[26:29], v[54:57]
	ds_read_b128 v[30:33], v116 offset:12288
	v_max3_f32 v114, v114, v72, v73
	s_nop 5
	v_max3_f32 v114, v114, v66, v67
	s_waitcnt lgkmcnt(0)
	v_mfma_f32_16x16x32_bf16 v[62:65], v[30:33], v[26:29], v[58:61]
	ds_read_b128 v[30:33], v116 offset:14336
	v_max3_f32 v114, v114, v68, v69
	s_nop 5
	v_max3_f32 v114, v114, v62, v63
	s_waitcnt lgkmcnt(0)
	v_mfma_f32_16x16x32_bf16 v[58:61], v[30:33], v[26:29], v[126:129]
	ds_read_b128 v[30:33], v116 offset:16384
	s_nop 1
	ds_read_b128 v[126:129], v116 offset:30720
	v_max3_f32 v114, v114, v64, v65
	s_waitcnt lgkmcnt(0)
; DI void unit_X(const Params& p, char* lds, int l, int chunk) {
;     ...
;         float mxv = -3.0e38f;
; #pragma unroll
;         for (int mt = 0; mt < 16; ++mt)
; #pragma unroll
;             for (int i = 0; i < 4; ++i) mxv = fmaxf(mxv, s[mt][i]);
;         mxv = fmaxf(mxv, __shfl_xor(mxv, 16));
;         mxv = fmaxf(mxv, __shfl_xor(mxv, 32));
;         float sum = 0.f;
; #pragma unroll
;         for (int mt = 0; mt < 16; ++mt)
; #pragma unroll
;             for (int i = 0; i < 4; ++i) { const float e = __builtin_amdgcn_exp2f(s[mt][i] - mxv); s[mt][i] = e; sum += e; }
	v_mfma_f32_16x16x32_bf16 v[54:57], v[30:33], v[26:29], v[146:149]
	ds_read_b128 v[30:33], v116 offset:18432
	v_max3_f32 v114, v114, v58, v59
	v_max3_f32 v114, v114, v60, v61
	s_waitcnt lgkmcnt(0)
	v_mfma_f32_16x16x32_bf16 v[50:53], v[30:33], v[26:29], v[154:157]
	ds_read_b128 v[30:33], v116 offset:20480
	s_nop 1
	v_max3_f32 v114, v114, v54, v55
	v_max3_f32 v114, v114, v56, v57
	s_waitcnt lgkmcnt(0)
	v_mfma_f32_16x16x32_bf16 v[46:49], v[30:33], v[26:29], v[158:161]
	ds_read_b128 v[30:33], v116 offset:22528
	v_max3_f32 v114, v114, v50, v51
	v_max3_f32 v114, v114, v52, v53
	s_waitcnt lgkmcnt(0)
	v_mfma_f32_16x16x32_bf16 v[42:45], v[30:33], v[26:29], v[162:165]
	ds_read_b128 v[30:33], v116 offset:24576
	s_nop 1
	v_max3_f32 v114, v114, v46, v47
	v_max3_f32 v114, v114, v48, v49
	s_waitcnt lgkmcnt(0)
	v_mfma_f32_16x16x32_bf16 v[38:41], v[30:33], v[26:29], v[166:169]
	ds_read_b128 v[30:33], v116 offset:26624
	v_max3_f32 v114, v114, v42, v43
	v_max3_f32 v114, v114, v44, v45
	s_waitcnt lgkmcnt(0)
	v_mfma_f32_16x16x32_bf16 v[34:37], v[30:33], v[26:29], v[170:173]
	ds_read_b128 v[30:33], v116 offset:28672
	s_nop 1
	v_max3_f32 v114, v114, v38, v39
	v_max3_f32 v114, v114, v40, v41
	s_waitcnt lgkmcnt(0)
	v_mfma_f32_16x16x32_bf16 v[30:33], v[30:33], v[26:29], v[174:177]
	s_nop 0
	v_max3_f32 v114, v114, v34, v35
	v_max3_f32 v114, v114, v36, v37
	s_nop 4
	v_max3_f32 v114, v114, v30, v31
	v_mfma_f32_16x16x32_bf16 v[26:29], v[126:129], v[26:29], v[178:181]
	v_max3_f32 v114, v114, v32, v33
	v_and_b32_e32 v126, 64, v214
	v_add_u32_e32 v126, 64, v126
	s_nop 4
	v_max3_f32 v114, v114, v26, v27
	v_max3_f32 v115, v114, v28, v29
	v_xor_b32_e32 v114, 16, v214
	v_cmp_lt_i32_e32 vcc, v114, v126
	s_nop 1
	v_cndmask_b32_e32 v114, v214, v114, vcc
	v_lshlrev_b32_e32 v114, 2, v114
	ds_bpermute_b32 v127, v114, v115
	s_waitcnt lgkmcnt(0)
	v_max_f32_e32 v127, v127, v127
	v_max_f32_e32 v127, v115, v127
	v_xor_b32_e32 v115, 32, v214
	v_cmp_lt_i32_e32 vcc, v115, v126
	s_nop 1
	v_cndmask_b32_e32 v115, v214, v115, vcc
	v_lshlrev_b32_e32 v115, 2, v115
	ds_bpermute_b32 v126, v115, v127
	s_waitcnt lgkmcnt(0)
	v_max_f32_e32 v126, v126, v126
	v_max_f32_e32 v128, v127, v126
	v_sub_f32_e32 v126, v182, v128
	v_exp_f32_e32 v129, v126
	v_sub_f32_e32 v127, v183, v128
	v_exp_f32_e32 v145, v127
	v_sub_f32_e32 v127, v184, v128
	v_exp_f32_e32 v147, v127
	v_sub_f32_e32 v127, v185, v128
	v_exp_f32_e32 v148, v127
	v_sub_f32_e32 v127, v186, v128
	v_add_f32_e32 v126, 0, v129
	v_exp_f32_e32 v149, v127
	v_sub_f32_e32 v127, v187, v128
	v_add_f32_e32 v126, v145, v126
	v_exp_f32_e32 v150, v127
	v_sub_f32_e32 v127, v188, v128
	v_add_f32_e32 v126, v147, v126
	v_exp_f32_e32 v151, v127
	v_sub_f32_e32 v127, v189, v128
	v_add_f32_e32 v126, v148, v126
	v_exp_f32_e32 v154, v127
	v_sub_f32_e32 v78, v78, v128
	v_add_f32_e32 v126, v149, v126
	v_exp_f32_e32 v78, v78
	v_add_f32_e32 v126, v150, v126
	v_add_f32_e32 v126, v151, v126
	v_add_f32_e32 v126, v154, v126
	v_sub_f32_e32 v79, v79, v128
	v_add_f32_e32 v127, v78, v126
	v_exp_f32_e32 v126, v79
	v_sub_f32_e32 v80, v80, v128
	v_exp_f32_e32 v80, v80
	v_sub_f32_e32 v81, v81, v128
	v_exp_f32_e32 v81, v81
	v_sub_f32_e32 v74, v74, v128
	v_add_f32_e32 v79, v126, v127
	v_exp_f32_e32 v127, v74
	v_sub_f32_e32 v75, v75, v128
	v_exp_f32_e32 v75, v75
	v_sub_f32_e32 v76, v76, v128
	v_add_f32_e32 v79, v80, v79
	v_exp_f32_e32 v76, v76
	v_sub_f32_e32 v77, v77, v128
	v_add_f32_e32 v79, v81, v79
	v_exp_f32_e32 v77, v77
	v_sub_f32_e32 v70, v70, v128
	v_add_f32_e32 v74, v127, v79
	v_exp_f32_e32 v70, v70
	v_sub_f32_e32 v71, v71, v128
	v_add_f32_e32 v74, v75, v74
	v_exp_f32_e32 v71, v71
	v_sub_f32_e32 v72, v72, v128
	v_add_f32_e32 v74, v76, v74
	v_exp_f32_e32 v72, v72
	v_sub_f32_e32 v73, v73, v128
	v_add_f32_e32 v74, v77, v74
	v_exp_f32_e32 v73, v73
	v_sub_f32_e32 v66, v66, v128
	v_add_f32_e32 v74, v70, v74
	v_exp_f32_e32 v66, v66
	v_sub_f32_e32 v67, v67, v128
	v_add_f32_e32 v74, v71, v74
	v_exp_f32_e32 v67, v67
	v_add_f32_e32 v74, v72, v74
	v_add_f32_e32 v74, v73, v74
	v_add_f32_e32 v74, v66, v74
	v_sub_f32_e32 v68, v68, v128
	v_add_f32_e32 v79, v67, v74
	v_exp_f32_e32 v74, v68
	v_sub_f32_e32 v69, v69, v128
	v_exp_f32_e32 v69, v69
	v_sub_f32_e32 v62, v62, v128
	v_exp_f32_e32 v62, v62
	v_sub_f32_e32 v63, v63, v128
	v_exp_f32_e32 v63, v63
	v_sub_f32_e32 v64, v64, v128
	v_add_f32_e32 v68, v74, v79
	v_exp_f32_e32 v64, v64
	v_sub_f32_e32 v65, v65, v128
	v_add_f32_e32 v68, v69, v68
	v_exp_f32_e32 v65, v65
	v_sub_f32_e32 v58, v58, v128
	v_add_f32_e32 v68, v62, v68
	v_exp_f32_e32 v58, v58
	v_sub_f32_e32 v59, v59, v128
	v_add_f32_e32 v68, v63, v68
	v_exp_f32_e32 v59, v59
	v_sub_f32_e32 v60, v60, v128
	v_add_f32_e32 v68, v64, v68
	v_exp_f32_e32 v60, v60
	v_sub_f32_e32 v61, v61, v128
	v_add_f32_e32 v68, v65, v68
	v_exp_f32_e32 v61, v61
	v_sub_f32_e32 v54, v54, v128
	v_add_f32_e32 v68, v58, v68
	v_exp_f32_e32 v54, v54
	v_sub_f32_e32 v55, v55, v128
	v_add_f32_e32 v68, v59, v68
	v_exp_f32_e32 v55, v55
	v_sub_f32_e32 v56, v56, v128
	v_add_f32_e32 v68, v60, v68
	v_exp_f32_e32 v56, v56
	v_sub_f32_e32 v57, v57, v128
	v_add_f32_e32 v68, v61, v68
	v_exp_f32_e32 v57, v57
	v_sub_f32_e32 v50, v50, v128
	v_add_f32_e32 v68, v54, v68
	v_exp_f32_e32 v50, v50
	v_sub_f32_e32 v51, v51, v128
	v_add_f32_e32 v68, v55, v68
	v_exp_f32_e32 v51, v51
	v_sub_f32_e32 v52, v52, v128
	v_add_f32_e32 v68, v56, v68
	v_exp_f32_e32 v52, v52
	v_sub_f32_e32 v53, v53, v128
	v_add_f32_e32 v68, v57, v68
	v_exp_f32_e32 v53, v53
	v_sub_f32_e32 v46, v46, v128
	v_add_f32_e32 v68, v50, v68
	v_exp_f32_e32 v46, v46
	v_sub_f32_e32 v47, v47, v128
	v_add_f32_e32 v68, v51, v68
	v_exp_f32_e32 v47, v47
	v_sub_f32_e32 v48, v48, v128
	v_add_f32_e32 v68, v52, v68
; DI unsigned pk2(float lo, float hi) { const f32x2 v = {lo, hi}; const bf16x2_t b = __builtin_convertvector(v, bf16x2_t); return __builtin_bit_cast(unsigned, b); }
; DI f32x4 mfma16(bf16x8 a, bf16x8 b, f32x4 c) { return __builtin_amdgcn_mfma_f32_16x16x32_bf16(a, b, c, 0, 0, 0); }
; DI void unit_X(const Params& p, char* lds, int l, int chunk) {
;     ...
;             for (int i = 0; i < 4; ++i) { const float e = __builtin_amdgcn_exp2f(s[mt][i] - mxv); s[mt][i] = e; sum += e; }
;         sum += __shfl_xor(sum, 16);
;         sum += __shfl_xor(sum, 32);
;         const float inv = 1.f / sum;
;         f32x4 o[4];
; #pragma unroll
;         for (int dt = 0; dt < 4; ++dt) o[dt] = (f32x4){0.f, 0.f, 0.f, 0.f};
; #pragma unroll
;         for (int ks = 0; ks < 8; ++ks) {
;             const f32x4 a = s[2 * ks], c = s[2 * ks + 1];
;             const u32x4 w = (u32x4){pk2(a[0], a[1]), pk2(a[2], a[3]), pk2(c[0], c[1]), pk2(c[2], c[3])};
;             const bf16x8 pb = __builtin_bit_cast(bf16x8, w);
; #pragma unroll
;             for (int dt = 0; dt < 4; ++dt) {
;                 const int row = 16 * dt + l15;
;                 const bf16x8 av = *(const bf16x8*)(vd + row * 512 + (((4 * ks + quad) ^ (row & 15)) << 4));
;                 o[dt] = mfma16(av, pb, o[dt]);
;             }
;         }
	v_exp_f32_e32 v48, v48
	v_sub_f32_e32 v49, v49, v128
	v_add_f32_e32 v68, v53, v68
	v_exp_f32_e32 v49, v49
	v_sub_f32_e32 v42, v42, v128
	v_add_f32_e32 v68, v46, v68
	v_exp_f32_e32 v42, v42
	v_sub_f32_e32 v43, v43, v128
	v_add_f32_e32 v68, v47, v68
	v_exp_f32_e32 v43, v43
	v_sub_f32_e32 v44, v44, v128
	v_add_f32_e32 v68, v48, v68
	v_exp_f32_e32 v44, v44
	v_sub_f32_e32 v45, v45, v128
	v_add_f32_e32 v68, v49, v68
	v_exp_f32_e32 v45, v45
	v_sub_f32_e32 v38, v38, v128
	v_add_f32_e32 v68, v42, v68
	v_exp_f32_e32 v38, v38
	v_sub_f32_e32 v39, v39, v128
	v_add_f32_e32 v68, v43, v68
	v_exp_f32_e32 v39, v39
	v_sub_f32_e32 v40, v40, v128
	v_add_f32_e32 v68, v44, v68
	v_exp_f32_e32 v40, v40
	v_sub_f32_e32 v41, v41, v128
	v_add_f32_e32 v68, v45, v68
	v_exp_f32_e32 v41, v41
	v_sub_f32_e32 v34, v34, v128
	v_add_f32_e32 v68, v38, v68
	v_exp_f32_e32 v34, v34
	v_sub_f32_e32 v35, v35, v128
	v_add_f32_e32 v68, v39, v68
	v_exp_f32_e32 v35, v35
	v_sub_f32_e32 v36, v36, v128
	v_add_f32_e32 v68, v40, v68
	v_exp_f32_e32 v36, v36
	v_sub_f32_e32 v37, v37, v128
	v_add_f32_e32 v68, v41, v68
	v_exp_f32_e32 v37, v37
	v_sub_f32_e32 v30, v30, v128
	v_add_f32_e32 v68, v34, v68
	v_exp_f32_e32 v30, v30
	v_sub_f32_e32 v31, v31, v128
	v_add_f32_e32 v68, v35, v68
	v_exp_f32_e32 v31, v31
	v_sub_f32_e32 v32, v32, v128
	v_add_f32_e32 v68, v36, v68
	v_exp_f32_e32 v32, v32
	v_sub_f32_e32 v33, v33, v128
	v_add_f32_e32 v68, v37, v68
	v_exp_f32_e32 v33, v33
	v_sub_f32_e32 v26, v26, v128
	v_add_f32_e32 v68, v30, v68
	v_exp_f32_e32 v26, v26
	v_sub_f32_e32 v27, v27, v128
	v_add_f32_e32 v68, v31, v68
	v_exp_f32_e32 v27, v27
	v_sub_f32_e32 v28, v28, v128
	v_add_f32_e32 v68, v32, v68
	v_exp_f32_e32 v28, v28
	v_sub_f32_e32 v29, v29, v128
	v_add_f32_e32 v68, v33, v68
	v_exp_f32_e32 v29, v29
	v_add_f32_e32 v68, v26, v68
	v_add_f32_e32 v68, v27, v68
	v_add_f32_e32 v68, v28, v68
	v_add_f32_e32 v68, v29, v68
	ds_bpermute_b32 v79, v114, v68
	v_cvt_pk_bf16_f32 v147, v147, v148
	v_cvt_pk_bf16_f32 v148, v149, v150
	v_cvt_pk_bf16_f32 v149, v151, v154
	v_cvt_pk_bf16_f32 v146, v129, v145
	s_waitcnt lgkmcnt(0)
	v_add_f32_e32 v68, v68, v79
	ds_bpermute_b32 v79, v115, v68
	v_cvt_pk_bf16_f32 v172, v127, v75
	v_bitop3_b32 v75, v136, v135, 4 bitop3:0x36
	v_cvt_pk_bf16_f32 v170, v78, v126
	v_cvt_pk_bf16_f32 v171, v80, v81
	s_waitcnt lgkmcnt(0)
	v_add_f32_e32 v68, v68, v79
	v_xor_b32_e32 v79, v136, v135
	v_lshlrev_b32_e32 v150, 4, v79
	v_add3_u32 v79, 0, v150, v130
	ds_read_b128 v[154:157], v79 offset:32768
	ds_read_b128 v[158:161], v79 offset:40960
	ds_read_b128 v[162:165], v79 offset:49152
	ds_read_b128 v[166:169], v79 offset:57344
	s_waitcnt lgkmcnt(0)
	v_mfma_f32_16x16x32_bf16 v[154:157], v[154:157], v[146:149], 0
	v_cvt_pk_bf16_f32 v173, v76, v77
	v_cvt_pk_bf16_f32 v70, v70, v71
	v_cvt_pk_bf16_f32 v71, v72, v73
	v_mfma_f32_16x16x32_bf16 v[158:161], v[158:161], v[146:149], 0
	v_cvt_pk_bf16_f32 v72, v66, v67
	v_bitop3_b32 v66, v136, v135, 8 bitop3:0x36
	v_cvt_pk_bf16_f32 v62, v62, v63
	v_mfma_f32_16x16x32_bf16 v[162:165], v[162:165], v[146:149], 0
	v_cvt_pk_bf16_f32 v63, v64, v65
	v_cvt_pk_bf16_f32 v64, v58, v59
	v_bitop3_b32 v58, v136, v135, 12 bitop3:0x36
	v_mfma_f32_16x16x32_bf16 v[166:169], v[166:169], v[146:149], 0
	v_lshlrev_b32_e32 v148, 4, v75
	v_add3_u32 v78, 0, v148, v130
	ds_read_b128 v[126:129], v78 offset:32768
	s_waitcnt lgkmcnt(0)
	v_mfma_f32_16x16x32_bf16 v[126:129], v[126:129], v[170:173], v[154:157]
	s_nop 2
	ds_read_b128 v[154:157], v78 offset:40960
	v_lshlrev_b32_e32 v146, 4, v66
	v_add3_u32 v77, 0, v146, v130
	s_waitcnt lgkmcnt(0)
	v_mfma_f32_16x16x32_bf16 v[154:157], v[154:157], v[170:173], v[158:161]
	s_nop 2
	ds_read_b128 v[158:161], v78 offset:49152
	v_lshlrev_b32_e32 v145, 4, v58
	v_add3_u32 v81, 0, v145, v130
	s_waitcnt lgkmcnt(0)
	v_mfma_f32_16x16x32_bf16 v[158:161], v[158:161], v[170:173], v[162:165]
	s_nop 2
	ds_read_b128 v[162:165], v78 offset:57344
	v_cvt_pk_bf16_f32 v65, v60, v61
	ds_read_b128 v[58:61], v81 offset:32768
	s_waitcnt lgkmcnt(0)
	v_mfma_f32_16x16x32_bf16 v[162:165], v[162:165], v[170:173], v[166:169]
	s_nop 2
	ds_read_b128 v[166:169], v77 offset:32768
	v_cvt_pk_bf16_f32 v73, v74, v69
	v_cvt_pk_bf16_f32 v54, v54, v55
	v_cvt_pk_bf16_f32 v55, v56, v57
	s_waitcnt lgkmcnt(0)
	v_mfma_f32_16x16x32_bf16 v[126:129], v[166:169], v[70:73], v[126:129]
	ds_read_b128 v[166:169], v77 offset:40960
	v_cvt_pk_bf16_f32 v56, v50, v51
	v_bitop3_b32 v50, v136, v135, 16 bitop3:0x36
	v_mfma_f32_16x16x32_bf16 v[58:61], v[58:61], v[62:65], v[126:129]
	v_lshlrev_b32_e32 v147, 4, v50
	v_cvt_pk_bf16_f32 v57, v52, v53
	v_cvt_pk_bf16_f32 v46, v46, v47
	s_nop 0
	ds_read_b128 v[126:129], v81 offset:40960
	s_waitcnt lgkmcnt(0)
	v_mfma_f32_16x16x32_bf16 v[154:157], v[166:169], v[70:73], v[154:157]
	ds_read_b128 v[166:169], v77 offset:49152
	v_cvt_pk_bf16_f32 v47, v48, v49
	v_cvt_pk_bf16_f32 v48, v42, v43
	v_mfma_f32_16x16x32_bf16 v[154:157], v[126:129], v[62:65], v[154:157]
	ds_read_b128 v[126:129], v81 offset:49152
	v_bitop3_b32 v42, v136, v135, 20 bitop3:0x36
	v_lshlrev_b32_e32 v149, 4, v42
	s_waitcnt lgkmcnt(0)
	v_mfma_f32_16x16x32_bf16 v[158:161], v[166:169], v[70:73], v[158:161]
	ds_read_b128 v[166:169], v77 offset:57344
	v_cvt_pk_bf16_f32 v49, v44, v45
	v_cvt_pk_bf16_f32 v38, v38, v39
	v_mfma_f32_16x16x32_bf16 v[158:161], v[126:129], v[62:65], v[158:161]
	ds_read_b128 v[126:129], v81 offset:57344
	v_cvt_pk_bf16_f32 v39, v40, v41
	v_cvt_pk_bf16_f32 v40, v34, v35
	s_waitcnt lgkmcnt(0)
; DI unsigned pk2(float lo, float hi) { const f32x2 v = {lo, hi}; const bf16x2_t b = __builtin_convertvector(v, bf16x2_t); return __builtin_bit_cast(unsigned, b); }
; DI float bf2f(unsigned b) { return __uint_as_float(b << 16); }
; DI f32x4 mfma16(bf16x8 a, bf16x8 b, f32x4 c) { return __builtin_amdgcn_mfma_f32_16x16x32_bf16(a, b, c, 0, 0, 0); }
; DI size_t y_off(int tok, int col) { return ((size_t)(((tok >> 6) * 32 + (col >> 5)) * 64 + (tok & 63))) * 32 + (col & 31); }
; DI void unit_X(const Params& p, char* lds, int l, int chunk) {
;     ...
;         const float inv = 1.f / sum;
;         f32x4 o[4];
; #pragma unroll
;         for (int dt = 0; dt < 4; ++dt) o[dt] = (f32x4){0.f, 0.f, 0.f, 0.f};
; #pragma unroll
;         for (int ks = 0; ks < 8; ++ks) {
;             const f32x4 a = s[2 * ks], c = s[2 * ks + 1];
;             const u32x4 w = (u32x4){pk2(a[0], a[1]), pk2(a[2], a[3]), pk2(c[0], c[1]), pk2(c[2], c[3])};
;             const bf16x8 pb = __builtin_bit_cast(bf16x8, w);
; #pragma unroll
;             for (int dt = 0; dt < 4; ++dt) {
;                 const int row = 16 * dt + l15;
;                 const bf16x8 av = *(const bf16x8*)(vd + row * 512 + (((4 * ks + quad) ^ (row & 15)) << 4));
;                 o[dt] = mfma16(av, pb, o[dt]);
;             }
;         }
; #pragma unroll
;         for (int dt = 0; dt < 4; ++dt) {
;             const int d = 16 * dt + 4 * quad;
;             const u32x2 gv = *(const u32x2*)(gx + (size_t)tok * 256 + 64 * h + d);
;             const float o0 = o[dt][0] * inv * bf2f(gv[0] & 0xffffu), o1 = o[dt][1] * inv * bf2f(gv[0] >> 16);
;             const float o2 = o[dt][2] * inv * bf2f(gv[1] & 0xffffu), o3 = o[dt][3] * inv * bf2f(gv[1] >> 16);
;             *(u32x2*)(yo + y_off(chunk * 128 + tok, 768 + h * 64 + d)) = (u32x2){pk2(o0, o1), pk2(o2, o3)};
;         }
	v_mfma_f32_16x16x32_bf16 v[70:73], v[166:169], v[70:73], v[162:165]
	v_bitop3_b32 v34, v136, v135, 24 bitop3:0x36
	v_lshlrev_b32_e32 v151, 4, v34
	v_cvt_pk_bf16_f32 v41, v36, v37
	v_mfma_f32_16x16x32_bf16 v[62:65], v[126:129], v[62:65], v[70:73]
	v_add3_u32 v126, 0, v147, v130
	ds_read_b128 v[50:53], v126 offset:32768
	s_nop 1
	ds_read_b128 v[70:73], v126 offset:49152
	v_add3_u32 v127, 0, v149, v130
	s_waitcnt lgkmcnt(0)
	v_mfma_f32_16x16x32_bf16 v[50:53], v[50:53], v[54:57], v[58:61]
	s_nop 2
	ds_read_b128 v[58:61], v126 offset:40960
	ds_read_b128 v[42:45], v127 offset:32768
	v_add3_u32 v128, 0, v151, v130
	s_waitcnt lgkmcnt(0)
	v_mfma_f32_16x16x32_bf16 v[58:61], v[58:61], v[54:57], v[154:157]
	s_nop 2
	ds_read_b128 v[154:157], v126 offset:57344
	ds_read_b128 v[34:37], v128 offset:32768
	v_lshl_or_b32 v76, v152, 5, v153
	v_mfma_f32_16x16x32_bf16 v[42:45], v[42:45], v[46:49], v[50:53]
	v_mov_b32_e32 v75, v1
	v_add3_u32 v80, s12, v137, v131
	s_nop 0
	ds_read_b128 v[50:53], v127 offset:40960
	v_mfma_f32_16x16x32_bf16 v[70:73], v[70:73], v[54:57], v[158:161]
	s_waitcnt lgkmcnt(0)
	v_mfma_f32_16x16x32_bf16 v[54:57], v[154:157], v[54:57], v[62:65]
	v_mfma_f32_16x16x32_bf16 v[50:53], v[50:53], v[46:49], v[58:61]
	s_nop 1
	ds_read_b128 v[62:65], v127 offset:57344
	ds_read_b128 v[58:61], v127 offset:49152
	s_waitcnt lgkmcnt(0)
	v_mfma_f32_16x16x32_bf16 v[58:61], v[58:61], v[46:49], v[70:73]
	s_nop 2
	v_lshlrev_b32_e32 v72, 1, v134
	v_mov_b32_e32 v73, v1
	v_lshl_add_u64 v[70:71], v[112:113], 0, v[72:73]
	global_load_dwordx2 v[228:229], v[70:71], off
	global_load_dwordx2 v[230:231], v[70:71], off offset:32
	global_load_dwordx2 v[232:233], v[70:71], off offset:64
	global_load_dwordx2 v[234:235], v[70:71], off offset:96
	v_mfma_f32_16x16x32_bf16 v[46:49], v[62:65], v[46:49], v[54:57]
	v_add3_u32 v112, s12, v144, v131
	s_nop 1
	ds_read_b128 v[54:57], v128 offset:57344
	v_mfma_f32_16x16x32_bf16 v[34:37], v[34:37], v[38:41], v[42:45]
	s_nop 2
	ds_read_b128 v[42:45], v128 offset:40960
	s_waitcnt lgkmcnt(0)
	v_mfma_f32_16x16x32_bf16 v[46:49], v[54:57], v[38:41], v[46:49]
	v_cvt_pk_bf16_f32 v56, v26, v27
	v_bitop3_b32 v26, v136, v135, 28 bitop3:0x36
	v_lshlrev_b32_e32 v135, 4, v26
	v_add3_u32 v129, 0, v135, v130
	v_cvt_pk_bf16_f32 v57, v28, v29
	ds_read_b128 v[26:29], v129 offset:32768
	v_mfma_f32_16x16x32_bf16 v[42:45], v[42:45], v[38:41], v[50:53]
	v_cvt_pk_bf16_f32 v54, v30, v31
	v_cvt_pk_bf16_f32 v55, v32, v33
	s_nop 0
	ds_read_b128 v[50:53], v128 offset:49152
	s_waitcnt lgkmcnt(0)
	v_mfma_f32_16x16x32_bf16 v[50:53], v[50:53], v[38:41], v[58:61]
	v_mfma_f32_16x16x32_bf16 v[38:41], v[26:29], v[54:57], v[34:37]
	ds_read_b128 v[26:29], v129 offset:40960
	s_waitcnt lgkmcnt(0)
	v_mfma_f32_16x16x32_bf16 v[34:37], v[26:29], v[54:57], v[42:45]
	ds_read_b128 v[26:29], v129 offset:49152
	s_nop 1
	v_div_scale_f32 v42, s[0:1], v68, v68, 1.0
	s_waitcnt lgkmcnt(0)
	v_mfma_f32_16x16x32_bf16 v[30:33], v[26:29], v[54:57], v[50:53]
	ds_read_b128 v[26:29], v129 offset:57344
	v_rcp_f32_e32 v43, v42
	s_add_u32 s0, s6, 0x10000
	s_waitcnt lgkmcnt(0)
	v_mfma_f32_16x16x32_bf16 v[26:29], v[26:29], v[54:57], v[46:49]
	v_fma_f32 v44, -v42, v43, 1.0
	v_fmac_f32_e32 v43, v44, v43
	v_div_scale_f32 v44, vcc, 1.0, v68, 1.0
	v_mul_f32_e32 v45, v44, v43
	v_fma_f32 v46, -v42, v45, v44
	v_fmac_f32_e32 v45, v46, v43
	v_fma_f32 v42, -v42, v45, v44
	v_div_fmas_f32 v42, v42, v43, v45
	v_div_fixup_f32 v42, v42, v68, 1.0
	v_pk_mul_f32 v[38:39], v[38:39], v[42:43] op_sel_hi:[1,0]
	v_pk_mul_f32 v[40:41], v[40:41], v[42:43] op_sel_hi:[1,0]
	v_pk_mul_f32 v[34:35], v[34:35], v[42:43] op_sel_hi:[1,0]
	v_pk_mul_f32 v[36:37], v[36:37], v[42:43] op_sel_hi:[1,0]
	v_pk_mul_f32 v[30:31], v[30:31], v[42:43] op_sel_hi:[1,0]
	v_pk_mul_f32 v[32:33], v[32:33], v[42:43] op_sel_hi:[1,0]
	v_pk_mul_f32 v[26:27], v[26:27], v[42:43] op_sel_hi:[1,0]
	v_pk_mul_f32 v[28:29], v[28:29], v[42:43] op_sel_hi:[1,0]
	s_addc_u32 s1, s7, 0
	s_add_u32 s14, s8, 0x10000
	s_addc_u32 s15, s9, 0
	s_waitcnt vmcnt(0)
	v_mov_b32_e32 v44, v228
	v_mov_b32_e32 v45, v229
	v_lshlrev_b32_e32 v46, 16, v44
	v_and_b32_e32 v47, 0xffff0000, v44
	v_lshlrev_b32_e32 v44, 16, v45
	v_and_b32_e32 v45, 0xffff0000, v45
	v_pk_mul_f32 v[38:39], v[38:39], v[46:47]
	v_pk_mul_f32 v[40:41], v[40:41], v[44:45]
	v_cvt_pk_bf16_f32 v38, v38, v39
	v_cvt_pk_bf16_f32 v39, v40, v41
	v_or_b32_e32 v40, 0x600, v76
	v_ashrrev_i32_e32 v41, 31, v40
	v_lshlrev_b64 v[40:41], 6, v[40:41]
	v_lshl_add_u64 v[40:41], s[54:55], 0, v[40:41]
	v_lshl_add_u64 v[40:41], v[40:41], 0, v[72:73]
	global_store_dwordx2 v[40:41], v[38:39], off
	s_nop 1
	v_mov_b32_e32 v38, v230
	v_mov_b32_e32 v39, v231
	v_lshlrev_b32_e32 v44, 16, v38
	v_and_b32_e32 v45, 0xffff0000, v38
	v_lshlrev_b32_e32 v38, 16, v39
	v_and_b32_e32 v39, 0xffff0000, v39
	v_pk_mul_f32 v[34:35], v[34:35], v[44:45]
	v_pk_mul_f32 v[36:37], v[36:37], v[38:39]
	v_cvt_pk_bf16_f32 v34, v34, v35
	v_cvt_pk_bf16_f32 v35, v36, v37
	global_store_dwordx2 v[40:41], v[34:35], off offset:32
	s_nop 1
	v_mov_b32_e32 v34, v232
	v_mov_b32_e32 v35, v233
	v_lshlrev_b32_e32 v36, 16, v34
	v_and_b32_e32 v37, 0xffff0000, v34
	v_lshlrev_b32_e32 v34, 16, v35
	v_and_b32_e32 v35, 0xffff0000, v35
	v_pk_mul_f32 v[30:31], v[30:31], v[36:37]
	v_pk_mul_f32 v[32:33], v[32:33], v[34:35]
	v_cvt_pk_bf16_f32 v30, v30, v31
	v_cvt_pk_bf16_f32 v31, v32, v33
	v_or_b32_e32 v32, 0x640, v76
	v_ashrrev_i32_e32 v33, 31, v32
	v_lshlrev_b64 v[32:33], 6, v[32:33]
	v_lshl_add_u64 v[32:33], s[54:55], 0, v[32:33]
	v_lshl_add_u64 v[34:35], v[32:33], 0, v[72:73]
	global_store_dwordx2 v[34:35], v[30:31], off
	s_nop 1
	v_mov_b32_e32 v30, v234
	v_mov_b32_e32 v31, v235
	v_lshlrev_b32_e32 v34, 16, v30
	v_and_b32_e32 v35, 0xffff0000, v30
	v_lshlrev_b32_e32 v30, 16, v31
	v_and_b32_e32 v31, 0xffff0000, v31
	v_pk_mul_f32 v[26:27], v[26:27], v[34:35]
	v_pk_mul_f32 v[28:29], v[28:29], v[30:31]
	v_cvt_pk_bf16_f32 v26, v26, v27
	v_cvt_pk_bf16_f32 v27, v28, v29
	v_bitop3_b32 v28, v134, 28, 16 bitop3:0xc8
	v_lshlrev_b32_e32 v74, 1, v28
	v_lshl_add_u64 v[28:29], v[32:33], 0, v[74:75]
	global_store_dwordx2 v[28:29], v[26:27], off
	s_waitcnt vmcnt(4)
	v_lshl_add_u64 v[26:27], s[0:1], 0, v[82:83]
	s_barrier
; DI f32x4 mfma16(bf16x8 a, bf16x8 b, f32x4 c) { return __builtin_amdgcn_mfma_f32_16x16x32_bf16(a, b, c, 0, 0, 0); }
; template <int N> DI void wait_vm() { asm volatile("s_waitcnt vmcnt(%0)" ::"n"(N) : "memory"); }
; DI void raw_barrier() { asm volatile("" ::: "memory"); __builtin_amdgcn_s_barrier(); asm volatile("" ::: "memory"); }
; DI void unit_X(const Params& p, char* lds, int l, int chunk) {
;     ...
; #pragma unroll
;     for (int h = 0; h < 4; ++h) {
;         wait_vm<0>();
;         raw_barrier();
;         if (h < 3) issue_kv(h + 1, (h + 1) & 1);
;         const char* kd = lds + (h & 1) * 65536;
;         const char* vd = kd + 32768;
;         f32x4 s[16];
; #pragma unroll
;         for (int mt = 0; mt < 16; ++mt) s[mt] = (f32x4){0.f, 0.f, 0.f, 0.f};
; #pragma unroll
;         for (int ks = 0; ks < 2; ++ks) {
; #pragma unroll
;             for (int mt = 0; mt < 16; ++mt) {
;                 const int row = 16 * mt + l15;
;                 const bf16x8 ak = *(const bf16x8*)(kd + row * 128 + (((4 * ks + quad) ^ ((row >> 1) & 7)) << 4));
;                 s[mt] = mfma16(ak, bq[h][ks], s[mt]);
;             }
;         }
	global_load_dwordx2 v[228:229], v[70:71], off offset:128
	global_load_dwordx2 v[230:231], v[70:71], off offset:160
	global_load_dwordx2 v[232:233], v[70:71], off offset:192
	global_load_dwordx2 v[234:235], v[70:71], off offset:224
	v_lshl_add_u64 v[26:27], v[26:27], 0, v[0:1]
	global_load_lds_dwordx4 v[26:27], off
	v_lshl_add_u64 v[26:27], s[14:15], 0, v[84:85]
	v_lshl_add_u64 v[26:27], v[26:27], 0, v[86:87]
	s_mov_b32 m0, s11
	v_readfirstlane_b32 s11, v138
	global_load_lds_dwordx4 v[26:27], off
	v_lshl_add_u64 v[26:27], s[0:1], 0, v[88:89]
	v_lshl_add_u64 v[26:27], v[26:27], 0, v[90:91]
	s_mov_b32 m0, s11
	v_readfirstlane_b32 s11, v139
	global_load_lds_dwordx4 v[26:27], off
	v_lshl_add_u64 v[26:27], s[14:15], 0, v[92:93]
	v_lshl_add_u64 v[26:27], v[26:27], 0, v[94:95]
	s_mov_b32 m0, s11
	v_readfirstlane_b32 s11, v140
	global_load_lds_dwordx4 v[26:27], off
	v_lshl_add_u64 v[26:27], s[0:1], 0, v[96:97]
	v_lshl_add_u64 v[26:27], v[26:27], 0, v[98:99]
	s_mov_b32 m0, s11
	v_readfirstlane_b32 s11, v141
	global_load_lds_dwordx4 v[26:27], off
	v_lshl_add_u64 v[26:27], s[14:15], 0, v[100:101]
	v_lshl_add_u64 v[26:27], v[26:27], 0, v[102:103]
	s_mov_b32 m0, s11
	s_nop 0
	global_load_lds_dwordx4 v[26:27], off
	v_lshl_add_u64 v[26:27], s[0:1], 0, v[104:105]
	v_readfirstlane_b32 s0, v142
	v_lshl_add_u64 v[26:27], v[26:27], 0, v[106:107]
	s_mov_b32 m0, s0
	v_readfirstlane_b32 s0, v143
	global_load_lds_dwordx4 v[26:27], off
	v_lshl_add_u64 v[26:27], s[14:15], 0, v[108:109]
	v_lshl_add_u64 v[26:27], v[26:27], 0, v[110:111]
	s_mov_b32 m0, s0
	s_nop 0
	global_load_lds_dwordx4 v[26:27], off
	ds_read_b128 v[50:53], v80 offset:12288
	ds_read_b128 v[54:57], v80 offset:14336
	s_waitcnt lgkmcnt(0)
	v_mfma_f32_16x16x32_bf16 v[136:139], v[54:57], v[22:25], 0
	ds_read_b128 v[54:57], v80 offset:16384
	ds_read_b128 v[26:29], v80
	ds_read_b128 v[30:33], v80 offset:2048
	s_waitcnt lgkmcnt(0)
	v_mfma_f32_16x16x32_bf16 v[140:143], v[54:57], v[22:25], 0
	ds_read_b128 v[54:57], v80 offset:18432
	ds_read_b128 v[34:37], v80 offset:4096
	ds_read_b128 v[38:41], v80 offset:6144
	s_waitcnt lgkmcnt(0)
	v_mfma_f32_16x16x32_bf16 v[152:155], v[54:57], v[22:25], 0
	ds_read_b128 v[54:57], v80 offset:20480
	ds_read_b128 v[42:45], v80 offset:8192
	ds_read_b128 v[46:49], v80 offset:10240
	s_waitcnt lgkmcnt(0)
	v_mfma_f32_16x16x32_bf16 v[156:159], v[54:57], v[22:25], 0
	ds_read_b128 v[54:57], v80 offset:22528
	s_waitcnt lgkmcnt(0)
	v_mfma_f32_16x16x32_bf16 v[160:163], v[54:57], v[22:25], 0
	ds_read_b128 v[54:57], v80 offset:24576
	s_waitcnt lgkmcnt(0)
	v_mfma_f32_16x16x32_bf16 v[164:167], v[54:57], v[22:25], 0
	ds_read_b128 v[54:57], v80 offset:26624
	s_waitcnt lgkmcnt(0)
	v_mfma_f32_16x16x32_bf16 v[168:171], v[54:57], v[22:25], 0
	ds_read_b128 v[54:57], v80 offset:28672
	s_waitcnt lgkmcnt(0)
	v_mfma_f32_16x16x32_bf16 v[172:175], v[54:57], v[22:25], 0
	ds_read_b128 v[54:57], v80 offset:30720
	v_mfma_f32_16x16x32_bf16 v[26:29], v[26:29], v[22:25], 0
	v_mfma_f32_16x16x32_bf16 v[30:33], v[30:33], v[22:25], 0
	v_mfma_f32_16x16x32_bf16 v[34:37], v[34:37], v[22:25], 0
	v_mfma_f32_16x16x32_bf16 v[38:41], v[38:41], v[22:25], 0
	v_mfma_f32_16x16x32_bf16 v[42:45], v[42:45], v[22:25], 0
	v_mfma_f32_16x16x32_bf16 v[46:49], v[46:49], v[22:25], 0
	v_mfma_f32_16x16x32_bf16 v[50:53], v[50:53], v[22:25], 0
	s_waitcnt lgkmcnt(0)
	v_mfma_f32_16x16x32_bf16 v[176:179], v[54:57], v[22:25], 0
	ds_read_b128 v[22:25], v112
	s_waitcnt lgkmcnt(0)
	v_mfma_f32_16x16x32_bf16 v[180:183], v[22:25], v[18:21], v[26:29]
	ds_read_b128 v[22:25], v112 offset:2048
	s_nop 6
	v_max3_f32 v113, v180, s13, v181
	s_waitcnt lgkmcnt(0)
	v_mfma_f32_16x16x32_bf16 v[184:187], v[22:25], v[18:21], v[30:33]
	ds_read_b128 v[22:25], v112 offset:4096
	v_max3_f32 v113, v113, v182, v183
	s_nop 5
	v_max3_f32 v113, v113, v184, v185
	s_waitcnt lgkmcnt(0)
	v_mfma_f32_16x16x32_bf16 v[188:191], v[22:25], v[18:21], v[34:37]
	ds_read_b128 v[22:25], v112 offset:6144
	v_max3_f32 v113, v113, v186, v187
	s_nop 5
	v_max3_f32 v113, v113, v188, v189
	s_waitcnt lgkmcnt(0)
	v_mfma_f32_16x16x32_bf16 v[66:69], v[22:25], v[18:21], v[38:41]
	ds_read_b128 v[22:25], v112 offset:8192
	v_max3_f32 v113, v113, v190, v191
	s_nop 5
	v_max3_f32 v113, v113, v66, v67
	s_waitcnt lgkmcnt(0)
	v_mfma_f32_16x16x32_bf16 v[62:65], v[22:25], v[18:21], v[42:45]
	ds_read_b128 v[22:25], v112 offset:10240
	v_max3_f32 v113, v113, v68, v69
	s_nop 5
	v_max3_f32 v113, v113, v62, v63
	s_waitcnt lgkmcnt(0)
	v_mfma_f32_16x16x32_bf16 v[58:61], v[22:25], v[18:21], v[46:49]
	ds_read_b128 v[22:25], v112 offset:12288
	v_max3_f32 v113, v113, v64, v65
	s_nop 5
	v_max3_f32 v113, v113, v58, v59
	s_waitcnt lgkmcnt(0)
	v_mfma_f32_16x16x32_bf16 v[54:57], v[22:25], v[18:21], v[50:53]
	ds_read_b128 v[22:25], v112 offset:14336
	v_max3_f32 v113, v113, v60, v61
	s_nop 5
	v_max3_f32 v113, v113, v54, v55
	s_waitcnt lgkmcnt(0)
	v_mfma_f32_16x16x32_bf16 v[50:53], v[22:25], v[18:21], v[136:139]
	ds_read_b128 v[22:25], v112 offset:16384
	s_nop 1
	ds_read_b128 v[136:139], v112 offset:30720
	v_max3_f32 v113, v113, v56, v57
	s_waitcnt lgkmcnt(0)
	v_mfma_f32_16x16x32_bf16 v[46:49], v[22:25], v[18:21], v[140:143]
	ds_read_b128 v[22:25], v112 offset:18432
	v_max3_f32 v113, v113, v50, v51
	v_max3_f32 v113, v113, v52, v53
	s_waitcnt lgkmcnt(0)
	v_mfma_f32_16x16x32_bf16 v[42:45], v[22:25], v[18:21], v[152:155]
	ds_read_b128 v[22:25], v112 offset:20480
	s_nop 1
	v_max3_f32 v113, v113, v46, v47
	v_max3_f32 v113, v113, v48, v49
	s_waitcnt lgkmcnt(0)
	v_mfma_f32_16x16x32_bf16 v[38:41], v[22:25], v[18:21], v[156:159]
	ds_read_b128 v[22:25], v112 offset:22528
	v_max3_f32 v113, v113, v42, v43
	v_max3_f32 v113, v113, v44, v45
	s_waitcnt lgkmcnt(0)
; DI void unit_X(const Params& p, char* lds, int l, int chunk) {
;     ...
;         float mxv = -3.0e38f;
; #pragma unroll
;         for (int mt = 0; mt < 16; ++mt)
; #pragma unroll
;             for (int i = 0; i < 4; ++i) mxv = fmaxf(mxv, s[mt][i]);
;         mxv = fmaxf(mxv, __shfl_xor(mxv, 16));
;         mxv = fmaxf(mxv, __shfl_xor(mxv, 32));
;         float sum = 0.f;
; #pragma unroll
;         for (int mt = 0; mt < 16; ++mt)
; #pragma unroll
;             for (int i = 0; i < 4; ++i) { const float e = __builtin_amdgcn_exp2f(s[mt][i] - mxv); s[mt][i] = e; sum += e; }
	v_mfma_f32_16x16x32_bf16 v[34:37], v[22:25], v[18:21], v[160:163]
	ds_read_b128 v[22:25], v112 offset:24576
	s_nop 1
	v_max3_f32 v113, v113, v38, v39
	v_max3_f32 v113, v113, v40, v41
	s_waitcnt lgkmcnt(0)
	v_mfma_f32_16x16x32_bf16 v[30:33], v[22:25], v[18:21], v[164:167]
	ds_read_b128 v[22:25], v112 offset:26624
	v_max3_f32 v113, v113, v34, v35
	v_max3_f32 v113, v113, v36, v37
	s_waitcnt lgkmcnt(0)
	v_mfma_f32_16x16x32_bf16 v[26:29], v[22:25], v[18:21], v[168:171]
	ds_read_b128 v[22:25], v112 offset:28672
	s_nop 1
	v_max3_f32 v113, v113, v30, v31
	v_max3_f32 v113, v113, v32, v33
	s_waitcnt lgkmcnt(0)
	v_mfma_f32_16x16x32_bf16 v[22:25], v[22:25], v[18:21], v[172:175]
	s_nop 0
	v_max3_f32 v113, v113, v26, v27
	v_max3_f32 v113, v113, v28, v29
	s_nop 4
	v_max3_f32 v113, v113, v22, v23
	v_mfma_f32_16x16x32_bf16 v[18:21], v[136:139], v[18:21], v[176:179]
	v_max3_f32 v113, v113, v24, v25
	s_nop 6
	v_max3_f32 v113, v113, v18, v19
	v_max3_f32 v113, v113, v20, v21
	ds_bpermute_b32 v131, v114, v113
	s_waitcnt lgkmcnt(0)
	v_max_f32_e32 v131, v131, v131
	v_max_f32_e32 v113, v113, v131
	ds_bpermute_b32 v131, v115, v113
	s_waitcnt lgkmcnt(0)
	v_max_f32_e32 v131, v131, v131
	v_max_f32_e32 v133, v113, v131
	v_sub_f32_e32 v113, v180, v133
	v_exp_f32_e32 v142, v113
	v_sub_f32_e32 v131, v181, v133
	v_exp_f32_e32 v143, v131
	v_sub_f32_e32 v131, v182, v133
	v_exp_f32_e32 v144, v131
	v_sub_f32_e32 v131, v183, v133
	v_exp_f32_e32 v152, v131
	v_sub_f32_e32 v131, v184, v133
	v_add_f32_e32 v113, 0, v142
	v_exp_f32_e32 v153, v131
	v_sub_f32_e32 v131, v185, v133
	v_add_f32_e32 v113, v143, v113
	v_exp_f32_e32 v154, v131
	v_sub_f32_e32 v131, v186, v133
	v_add_f32_e32 v113, v144, v113
	v_exp_f32_e32 v155, v131
	v_sub_f32_e32 v131, v187, v133
	v_add_f32_e32 v113, v152, v113
	v_exp_f32_e32 v156, v131
	v_add_f32_e32 v113, v153, v113
	v_add_f32_e32 v113, v154, v113
	v_add_f32_e32 v113, v155, v113
	v_add_f32_e32 v131, v156, v113
	v_sub_f32_e32 v113, v188, v133
	v_exp_f32_e32 v113, v113
	v_sub_f32_e32 v134, v190, v133
	v_exp_f32_e32 v134, v134
	v_sub_f32_e32 v136, v191, v133
	v_add_f32_e32 v132, v113, v131
	v_sub_f32_e32 v131, v189, v133
	v_exp_f32_e32 v131, v131
	v_exp_f32_e32 v137, v136
	v_sub_f32_e32 v66, v66, v133
	v_exp_f32_e32 v138, v66
	v_sub_f32_e32 v67, v67, v133
	v_add_f32_e32 v132, v131, v132
	v_exp_f32_e32 v139, v67
	v_sub_f32_e32 v67, v68, v133
	v_add_f32_e32 v132, v134, v132
	v_exp_f32_e32 v140, v67
	v_sub_f32_e32 v67, v69, v133
	v_add_f32_e32 v132, v137, v132
	v_exp_f32_e32 v141, v67
	v_add_f32_e32 v66, v138, v132
	v_add_f32_e32 v66, v139, v66
	v_add_f32_e32 v66, v140, v66
	v_sub_f32_e32 v62, v62, v133
	v_add_f32_e32 v67, v141, v66
	v_exp_f32_e32 v66, v62
	v_sub_f32_e32 v63, v63, v133
	v_sub_f32_e32 v58, v58, v133
	v_exp_f32_e32 v58, v58
	v_add_f32_e32 v62, v66, v67
	v_exp_f32_e32 v67, v63
	v_sub_f32_e32 v63, v64, v133
	v_exp_f32_e32 v64, v63
	v_sub_f32_e32 v63, v65, v133
	v_exp_f32_e32 v65, v63
	v_sub_f32_e32 v59, v59, v133
	v_add_f32_e32 v62, v67, v62
	v_exp_f32_e32 v68, v59
	v_sub_f32_e32 v60, v60, v133
	v_add_f32_e32 v62, v64, v62
	v_exp_f32_e32 v132, v60
	v_sub_f32_e32 v60, v61, v133
	v_add_f32_e32 v62, v65, v62
	v_exp_f32_e32 v136, v60
	v_sub_f32_e32 v54, v54, v133
	v_add_f32_e32 v62, v58, v62
	v_exp_f32_e32 v54, v54
	v_sub_f32_e32 v55, v55, v133
	v_add_f32_e32 v59, v68, v62
	v_exp_f32_e32 v55, v55
	v_sub_f32_e32 v56, v56, v133
	v_add_f32_e32 v59, v132, v59
	v_exp_f32_e32 v56, v56
	v_sub_f32_e32 v57, v57, v133
	v_add_f32_e32 v59, v136, v59
	v_exp_f32_e32 v57, v57
	v_sub_f32_e32 v50, v50, v133
	v_add_f32_e32 v59, v54, v59
	v_exp_f32_e32 v50, v50
	v_sub_f32_e32 v51, v51, v133
	v_add_f32_e32 v59, v55, v59
	v_exp_f32_e32 v51, v51
	v_sub_f32_e32 v52, v52, v133
	v_add_f32_e32 v59, v56, v59
	v_exp_f32_e32 v52, v52
	v_sub_f32_e32 v53, v53, v133
	v_add_f32_e32 v59, v57, v59
	v_exp_f32_e32 v53, v53
	v_sub_f32_e32 v46, v46, v133
	v_add_f32_e32 v59, v50, v59
	v_exp_f32_e32 v46, v46
	v_sub_f32_e32 v47, v47, v133
	v_add_f32_e32 v59, v51, v59
	v_exp_f32_e32 v47, v47
	v_sub_f32_e32 v48, v48, v133
	v_add_f32_e32 v59, v52, v59
	v_exp_f32_e32 v48, v48
	v_sub_f32_e32 v49, v49, v133
	v_add_f32_e32 v59, v53, v59
	v_exp_f32_e32 v49, v49
	v_sub_f32_e32 v42, v42, v133
	v_add_f32_e32 v59, v46, v59
	v_exp_f32_e32 v42, v42
	v_sub_f32_e32 v43, v43, v133
	v_add_f32_e32 v59, v47, v59
	v_exp_f32_e32 v43, v43
	v_sub_f32_e32 v44, v44, v133
	v_add_f32_e32 v59, v48, v59
	v_exp_f32_e32 v44, v44
	v_sub_f32_e32 v45, v45, v133
	v_add_f32_e32 v59, v49, v59
	v_exp_f32_e32 v45, v45
	v_sub_f32_e32 v38, v38, v133
	v_add_f32_e32 v59, v42, v59
	v_exp_f32_e32 v38, v38
	v_sub_f32_e32 v39, v39, v133
	v_add_f32_e32 v59, v43, v59
	v_exp_f32_e32 v39, v39
	v_sub_f32_e32 v40, v40, v133
	v_add_f32_e32 v59, v44, v59
	v_exp_f32_e32 v40, v40
	v_sub_f32_e32 v41, v41, v133
	v_add_f32_e32 v59, v45, v59
	v_exp_f32_e32 v41, v41
	v_sub_f32_e32 v34, v34, v133
	v_add_f32_e32 v59, v38, v59
	v_exp_f32_e32 v34, v34
	v_sub_f32_e32 v35, v35, v133
	v_add_f32_e32 v59, v39, v59
	v_exp_f32_e32 v35, v35
	v_sub_f32_e32 v36, v36, v133
	v_add_f32_e32 v59, v40, v59
	v_exp_f32_e32 v36, v36
	v_sub_f32_e32 v37, v37, v133
	v_add_f32_e32 v59, v41, v59
	v_exp_f32_e32 v37, v37
	v_sub_f32_e32 v30, v30, v133
	v_add_f32_e32 v59, v34, v59
	v_exp_f32_e32 v30, v30
	v_sub_f32_e32 v31, v31, v133
	v_add_f32_e32 v59, v35, v59
	v_exp_f32_e32 v31, v31
	v_sub_f32_e32 v32, v32, v133
	v_add_f32_e32 v59, v36, v59
	v_exp_f32_e32 v32, v32
	v_sub_f32_e32 v33, v33, v133
	v_add_f32_e32 v59, v37, v59
	v_exp_f32_e32 v33, v33
	v_sub_f32_e32 v26, v26, v133
	v_add_f32_e32 v59, v30, v59
	v_exp_f32_e32 v26, v26
	v_sub_f32_e32 v27, v27, v133
	v_add_f32_e32 v59, v31, v59
	v_exp_f32_e32 v27, v27
	v_sub_f32_e32 v28, v28, v133
	v_add_f32_e32 v59, v32, v59
	v_exp_f32_e32 v28, v28
	v_sub_f32_e32 v29, v29, v133
	v_add_f32_e32 v59, v33, v59
	v_exp_f32_e32 v29, v29
	v_sub_f32_e32 v22, v22, v133
	v_add_f32_e32 v59, v26, v59
	v_exp_f32_e32 v22, v22
	v_sub_f32_e32 v23, v23, v133
	v_add_f32_e32 v59, v27, v59
	v_exp_f32_e32 v23, v23
	v_sub_f32_e32 v24, v24, v133
	v_add_f32_e32 v59, v28, v59
	v_exp_f32_e32 v24, v24
	v_sub_f32_e32 v25, v25, v133
	v_add_f32_e32 v59, v29, v59
	v_exp_f32_e32 v25, v25
	v_sub_f32_e32 v18, v18, v133
	v_add_f32_e32 v59, v22, v59
	v_exp_f32_e32 v60, v18
	v_sub_f32_e32 v19, v19, v133
	v_add_f32_e32 v59, v23, v59
	v_exp_f32_e32 v61, v19
	v_sub_f32_e32 v19, v20, v133
	v_add_f32_e32 v59, v24, v59
	v_exp_f32_e32 v69, v19
	v_sub_f32_e32 v19, v21, v133
	v_add_f32_e32 v59, v25, v59
	v_exp_f32_e32 v133, v19
	v_add_f32_e32 v18, v60, v59
	v_add_f32_e32 v18, v61, v18
	v_add_f32_e32 v18, v69, v18
	v_add_f32_e32 v18, v133, v18
	ds_bpermute_b32 v19, v114, v18
	v_add3_u32 v62, s10, v150, v130
	v_cvt_pk_bf16_f32 v20, v153, v154
	v_cvt_pk_bf16_f32 v21, v155, v156
	ds_read_b128 v[156:159], v62 offset:8192
	s_waitcnt lgkmcnt(0)
; DI unsigned pk2(float lo, float hi) { const f32x2 v = {lo, hi}; const bf16x2_t b = __builtin_convertvector(v, bf16x2_t); return __builtin_bit_cast(unsigned, b); }
; DI f32x4 mfma16(bf16x8 a, bf16x8 b, f32x4 c) { return __builtin_amdgcn_mfma_f32_16x16x32_bf16(a, b, c, 0, 0, 0); }
; DI void unit_X(const Params& p, char* lds, int l, int chunk) {
;     ...
;             for (int i = 0; i < 4; ++i) { const float e = __builtin_amdgcn_exp2f(s[mt][i] - mxv); s[mt][i] = e; sum += e; }
;         sum += __shfl_xor(sum, 16);
;         sum += __shfl_xor(sum, 32);
;         const float inv = 1.f / sum;
;         f32x4 o[4];
; #pragma unroll
;         for (int dt = 0; dt < 4; ++dt) o[dt] = (f32x4){0.f, 0.f, 0.f, 0.f};
; #pragma unroll
;         for (int ks = 0; ks < 8; ++ks) {
;             const f32x4 a = s[2 * ks], c = s[2 * ks + 1];
;             const u32x4 w = (u32x4){pk2(a[0], a[1]), pk2(a[2], a[3]), pk2(c[0], c[1]), pk2(c[2], c[3])};
;             const bf16x8 pb = __builtin_bit_cast(bf16x8, w);
; #pragma unroll
;             for (int dt = 0; dt < 4; ++dt) {
;                 const int row = 16 * dt + l15;
;                 const bf16x8 av = *(const bf16x8*)(vd + row * 512 + (((4 * ks + quad) ^ (row & 15)) << 4));
;                 o[dt] = mfma16(av, pb, o[dt]);
;             }
;         }
	v_add_f32_e32 v18, v18, v19
	ds_bpermute_b32 v19, v115, v18
	ds_read_b128 v[160:163], v62 offset:16384
	ds_read_b128 v[164:167], v62 offset:24576
	v_add3_u32 v63, s10, v148, v130
	v_cvt_pk_bf16_f32 v54, v54, v55
	s_waitcnt lgkmcnt(0)
	v_add_f32_e32 v59, v18, v19
	v_cvt_pk_bf16_f32 v19, v144, v152
	ds_read_b128 v[152:155], v62
	v_cvt_pk_bf16_f32 v18, v142, v143
	v_cvt_pk_bf16_f32 v55, v56, v57
	v_cvt_pk_bf16_f32 v56, v50, v51
	s_waitcnt lgkmcnt(0)
	v_mfma_f32_16x16x32_bf16 v[152:155], v[152:155], v[18:21], 0
	v_cvt_pk_bf16_f32 v57, v52, v53
	v_cvt_pk_bf16_f32 v46, v46, v47
	v_cvt_pk_bf16_f32 v47, v48, v49
	v_mfma_f32_16x16x32_bf16 v[156:159], v[156:159], v[18:21], 0
	v_cvt_pk_bf16_f32 v48, v42, v43
	v_cvt_pk_bf16_f32 v49, v44, v45
	v_cvt_pk_bf16_f32 v38, v38, v39
	v_mfma_f32_16x16x32_bf16 v[160:163], v[160:163], v[18:21], 0
	v_cvt_pk_bf16_f32 v39, v40, v41
	v_cvt_pk_bf16_f32 v40, v34, v35
	v_cvt_pk_bf16_f32 v41, v36, v37
	v_mfma_f32_16x16x32_bf16 v[18:21], v[164:167], v[18:21], 0
	v_cvt_pk_bf16_f32 v166, v138, v139
	v_cvt_pk_bf16_f32 v167, v140, v141
	ds_read_b128 v[138:141], v63
	v_cvt_pk_bf16_f32 v164, v113, v131
	v_cvt_pk_bf16_f32 v165, v134, v137
	v_cvt_pk_bf16_f32 v30, v30, v31
	v_cvt_pk_bf16_f32 v31, v32, v33
	s_waitcnt lgkmcnt(0)
	v_mfma_f32_16x16x32_bf16 v[138:141], v[138:141], v[164:167], v[152:155]
	s_nop 2
	ds_read_b128 v[152:155], v63 offset:8192
	v_cvt_pk_bf16_f32 v32, v26, v27
	v_cvt_pk_bf16_f32 v33, v28, v29
	s_waitcnt lgkmcnt(0)
	v_mfma_f32_16x16x32_bf16 v[152:155], v[152:155], v[164:167], v[156:159]
	s_nop 2
	ds_read_b128 v[156:159], v63 offset:16384
	s_waitcnt lgkmcnt(0)
	v_mfma_f32_16x16x32_bf16 v[156:159], v[156:159], v[164:167], v[160:163]
	s_nop 2
	ds_read_b128 v[160:163], v63 offset:24576
	s_waitcnt lgkmcnt(0)
	v_mfma_f32_16x16x32_bf16 v[18:21], v[160:163], v[164:167], v[18:21]
	v_cvt_pk_bf16_f32 v161, v64, v65
	v_add3_u32 v64, s10, v146, v130
	ds_read_b128 v[164:167], v64
	v_add3_u32 v65, s10, v145, v130
	ds_read_b128 v[50:53], v65
	v_cvt_pk_bf16_f32 v160, v66, v67
	v_cvt_pk_bf16_f32 v162, v58, v68
	v_cvt_pk_bf16_f32 v163, v132, v136
	v_add3_u32 v66, s10, v147, v130
	ds_read_b128 v[42:45], v66
	s_waitcnt lgkmcnt(0)
	v_mfma_f32_16x16x32_bf16 v[136:139], v[164:167], v[160:163], v[138:141]
	v_add3_u32 v67, s10, v149, v130
	ds_read_b128 v[34:37], v67
	s_nop 0
	ds_read_b128 v[140:143], v64 offset:8192
	v_mfma_f32_16x16x32_bf16 v[50:53], v[50:53], v[54:57], v[136:139]
	v_add3_u32 v68, s10, v151, v130
	ds_read_b128 v[26:29], v68
	s_nop 0
	ds_read_b128 v[136:139], v65 offset:8192
	s_waitcnt lgkmcnt(0)
	v_mfma_f32_16x16x32_bf16 v[140:143], v[140:143], v[160:163], v[152:155]
	s_nop 2
	ds_read_b128 v[152:155], v64 offset:16384
	v_mfma_f32_16x16x32_bf16 v[136:139], v[136:139], v[54:57], v[140:143]
	s_nop 2
	ds_read_b128 v[140:143], v65 offset:16384
	s_waitcnt lgkmcnt(0)
	v_mfma_f32_16x16x32_bf16 v[152:155], v[152:155], v[160:163], v[156:159]
	s_nop 2
	ds_read_b128 v[156:159], v64 offset:24576
	v_mfma_f32_16x16x32_bf16 v[140:143], v[140:143], v[54:57], v[152:155]
	s_nop 2
	ds_read_b128 v[152:155], v65 offset:24576
	s_waitcnt lgkmcnt(0)
	v_mfma_f32_16x16x32_bf16 v[18:21], v[156:159], v[160:163], v[18:21]
	v_mfma_f32_16x16x32_bf16 v[18:21], v[152:155], v[54:57], v[18:21]
	ds_read_b128 v[54:57], v66 offset:16384
	v_mfma_f32_16x16x32_bf16 v[42:45], v[42:45], v[46:49], v[50:53]
	s_nop 2
	ds_read_b128 v[50:53], v66 offset:8192
	s_waitcnt lgkmcnt(0)
	v_mfma_f32_16x16x32_bf16 v[50:53], v[50:53], v[46:49], v[136:139]
	s_nop 2
	ds_read_b128 v[136:139], v66 offset:24576
	v_mfma_f32_16x16x32_bf16 v[34:37], v[34:37], v[38:41], v[42:45]
	s_nop 2
	ds_read_b128 v[42:45], v67 offset:8192
	v_mfma_f32_16x16x32_bf16 v[54:57], v[54:57], v[46:49], v[140:143]
	s_waitcnt lgkmcnt(0)
	v_mfma_f32_16x16x32_bf16 v[18:21], v[136:139], v[46:49], v[18:21]
	ds_read_b128 v[46:49], v67 offset:16384
	v_mfma_f32_16x16x32_bf16 v[42:45], v[42:45], v[38:41], v[50:53]
	s_nop 2
	ds_read_b128 v[50:53], v67 offset:24576
	s_waitcnt lgkmcnt(0)
	v_mfma_f32_16x16x32_bf16 v[46:49], v[46:49], v[38:41], v[54:57]
	v_mfma_f32_16x16x32_bf16 v[18:21], v[50:53], v[38:41], v[18:21]
	ds_read_b128 v[38:41], v68 offset:16384
	v_mfma_f32_16x16x32_bf16 v[26:29], v[26:29], v[30:33], v[34:37]
	s_nop 2
	ds_read_b128 v[34:37], v68 offset:8192
	s_waitcnt lgkmcnt(0)
	v_mfma_f32_16x16x32_bf16 v[34:37], v[34:37], v[30:33], v[42:45]
	s_nop 2
	ds_read_b128 v[42:45], v68 offset:24576
	s_waitcnt lgkmcnt(0)
	v_mfma_f32_16x16x32_bf16 v[18:21], v[42:45], v[30:33], v[18:21]
	v_cvt_pk_bf16_f32 v45, v69, v133
	v_add3_u32 v69, s10, v135, v130
	v_cvt_pk_bf16_f32 v42, v22, v23
	v_cvt_pk_bf16_f32 v43, v24, v25
	ds_read_b128 v[22:25], v69
	v_cvt_pk_bf16_f32 v44, v60, v61
	v_mfma_f32_16x16x32_bf16 v[38:41], v[38:41], v[30:33], v[46:49]
	s_waitcnt lgkmcnt(0)
	v_mfma_f32_16x16x32_bf16 v[30:33], v[22:25], v[42:45], v[26:29]
	ds_read_b128 v[22:25], v69 offset:8192
	s_waitcnt lgkmcnt(0)
	v_mfma_f32_16x16x32_bf16 v[26:29], v[22:25], v[42:45], v[34:37]
	ds_read_b128 v[22:25], v69 offset:16384
	s_nop 1
	ds_read_b128 v[34:37], v69 offset:24576
	s_waitcnt lgkmcnt(0)
; DI unsigned pk2(float lo, float hi) { const f32x2 v = {lo, hi}; const bf16x2_t b = __builtin_convertvector(v, bf16x2_t); return __builtin_bit_cast(unsigned, b); }
; DI float bf2f(unsigned b) { return __uint_as_float(b << 16); }
; DI f32x4 mfma16(bf16x8 a, bf16x8 b, f32x4 c) { return __builtin_amdgcn_mfma_f32_16x16x32_bf16(a, b, c, 0, 0, 0); }
; DI void unit_X(const Params& p, char* lds, int l, int chunk) {
;     ...
;         wait_vm<0>();
;         raw_barrier();
;         if (h < 3) issue_kv(h + 1, (h + 1) & 1);
;         const char* kd = lds + (h & 1) * 65536;
;         const char* vd = kd + 32768;
;         f32x4 s[16];
; #pragma unroll
;         for (int mt = 0; mt < 16; ++mt) s[mt] = (f32x4){0.f, 0.f, 0.f, 0.f};
; #pragma unroll
;         for (int ks = 0; ks < 2; ++ks) {
; #pragma unroll
;             for (int mt = 0; mt < 16; ++mt) {
;                 const int row = 16 * mt + l15;
;                 const bf16x8 ak = *(const bf16x8*)(kd + row * 128 + (((4 * ks + quad) ^ ((row >> 1) & 7)) << 4));
;                 s[mt] = mfma16(ak, bq[h][ks], s[mt]);
;             }
;         }
;     ...
;         const float inv = 1.f / sum;
;         f32x4 o[4];
; #pragma unroll
;         for (int dt = 0; dt < 4; ++dt) o[dt] = (f32x4){0.f, 0.f, 0.f, 0.f};
; #pragma unroll
;         for (int ks = 0; ks < 8; ++ks) {
;             const f32x4 a = s[2 * ks], c = s[2 * ks + 1];
;             const u32x4 w = (u32x4){pk2(a[0], a[1]), pk2(a[2], a[3]), pk2(c[0], c[1]), pk2(c[2], c[3])};
;             const bf16x8 pb = __builtin_bit_cast(bf16x8, w);
; #pragma unroll
;             for (int dt = 0; dt < 4; ++dt) {
;                 const int row = 16 * dt + l15;
;                 const bf16x8 av = *(const bf16x8*)(vd + row * 512 + (((4 * ks + quad) ^ (row & 15)) << 4));
;                 o[dt] = mfma16(av, pb, o[dt]);
;             }
;         }
; #pragma unroll
;         for (int dt = 0; dt < 4; ++dt) {
;             const int d = 16 * dt + 4 * quad;
;             const u32x2 gv = *(const u32x2*)(gx + (size_t)tok * 256 + 64 * h + d);
;             const float o0 = o[dt][0] * inv * bf2f(gv[0] & 0xffffu), o1 = o[dt][1] * inv * bf2f(gv[0] >> 16);
;             const float o2 = o[dt][2] * inv * bf2f(gv[1] & 0xffffu), o3 = o[dt][3] * inv * bf2f(gv[1] >> 16);
;             *(u32x2*)(yo + y_off(chunk * 128 + tok, 768 + h * 64 + d)) = (u32x2){pk2(o0, o1), pk2(o2, o3)};
;         }
	v_mfma_f32_16x16x32_bf16 v[18:21], v[34:37], v[42:45], v[18:21]
	v_div_scale_f32 v34, s[0:1], v59, v59, 1.0
	v_rcp_f32_e32 v35, v34
	v_mfma_f32_16x16x32_bf16 v[22:25], v[22:25], v[42:45], v[38:41]
	s_add_u32 s0, s6, 0x18000
	s_addc_u32 s1, s7, 0
	v_fma_f32 v36, -v34, v35, 1.0
	v_fmac_f32_e32 v35, v36, v35
	v_div_scale_f32 v36, vcc, 1.0, v59, 1.0
	v_mul_f32_e32 v37, v36, v35
	v_fma_f32 v38, -v34, v37, v36
	v_fmac_f32_e32 v37, v38, v35
	v_fma_f32 v34, -v34, v37, v36
	v_div_fmas_f32 v34, v34, v35, v37
	v_div_fixup_f32 v34, v34, v59, 1.0
	v_pk_mul_f32 v[30:31], v[30:31], v[34:35] op_sel_hi:[1,0]
	v_pk_mul_f32 v[32:33], v[32:33], v[34:35] op_sel_hi:[1,0]
	v_pk_mul_f32 v[26:27], v[26:27], v[34:35] op_sel_hi:[1,0]
	v_pk_mul_f32 v[28:29], v[28:29], v[34:35] op_sel_hi:[1,0]
	v_pk_mul_f32 v[22:23], v[22:23], v[34:35] op_sel_hi:[1,0]
	v_pk_mul_f32 v[24:25], v[24:25], v[34:35] op_sel_hi:[1,0]
	v_pk_mul_f32 v[18:19], v[18:19], v[34:35] op_sel_hi:[1,0]
	v_pk_mul_f32 v[20:21], v[20:21], v[34:35] op_sel_hi:[1,0]
	s_add_u32 s6, s8, 0x18000
	v_readfirstlane_b32 s8, v118
	s_addc_u32 s7, s9, 0
	s_mov_b32 m0, s8
	v_readfirstlane_b32 s8, v119
	s_waitcnt vmcnt(0)
	v_mov_b32_e32 v36, v228
	v_mov_b32_e32 v37, v229
	v_lshlrev_b32_e32 v38, 16, v36
	v_and_b32_e32 v39, 0xffff0000, v36
	v_lshlrev_b32_e32 v36, 16, v37
	v_and_b32_e32 v37, 0xffff0000, v37
	v_pk_mul_f32 v[30:31], v[30:31], v[38:39]
	v_pk_mul_f32 v[32:33], v[32:33], v[36:37]
	v_cvt_pk_bf16_f32 v30, v30, v31
	v_cvt_pk_bf16_f32 v31, v32, v33
	v_or_b32_e32 v32, 0x680, v76
	v_ashrrev_i32_e32 v33, 31, v32
	v_lshlrev_b64 v[32:33], 6, v[32:33]
	v_lshl_add_u64 v[32:33], s[54:55], 0, v[32:33]
	v_lshl_add_u64 v[32:33], v[32:33], 0, v[72:73]
	global_store_dwordx2 v[32:33], v[30:31], off
	s_nop 1
	v_mov_b32_e32 v30, v230
	v_mov_b32_e32 v31, v231
	v_lshlrev_b32_e32 v36, 16, v30
	v_and_b32_e32 v37, 0xffff0000, v30
	v_lshlrev_b32_e32 v30, 16, v31
	v_and_b32_e32 v31, 0xffff0000, v31
	v_pk_mul_f32 v[26:27], v[26:27], v[36:37]
	v_pk_mul_f32 v[28:29], v[28:29], v[30:31]
	v_cvt_pk_bf16_f32 v26, v26, v27
	v_cvt_pk_bf16_f32 v27, v28, v29
	global_store_dwordx2 v[32:33], v[26:27], off offset:32
	s_nop 1
	v_mov_b32_e32 v26, v232
	v_mov_b32_e32 v27, v233
	v_lshlrev_b32_e32 v28, 16, v26
	v_and_b32_e32 v29, 0xffff0000, v26
	v_lshlrev_b32_e32 v26, 16, v27
	v_and_b32_e32 v27, 0xffff0000, v27
	v_pk_mul_f32 v[22:23], v[22:23], v[28:29]
	v_pk_mul_f32 v[24:25], v[24:25], v[26:27]
	v_cvt_pk_bf16_f32 v22, v22, v23
	v_cvt_pk_bf16_f32 v23, v24, v25
	v_or_b32_e32 v24, 0x6c0, v76
	v_ashrrev_i32_e32 v25, 31, v24
	v_lshlrev_b64 v[24:25], 6, v[24:25]
	v_lshl_add_u64 v[24:25], s[54:55], 0, v[24:25]
	v_lshl_add_u64 v[26:27], v[24:25], 0, v[72:73]
	global_store_dwordx2 v[26:27], v[22:23], off
	s_nop 1
	v_mov_b32_e32 v22, v234
	v_mov_b32_e32 v23, v235
	v_lshlrev_b32_e32 v26, 16, v22
	v_and_b32_e32 v27, 0xffff0000, v22
	v_lshlrev_b32_e32 v22, 16, v23
	v_and_b32_e32 v23, 0xffff0000, v23
	v_pk_mul_f32 v[18:19], v[18:19], v[26:27]
	v_pk_mul_f32 v[20:21], v[20:21], v[22:23]
	v_cvt_pk_bf16_f32 v18, v18, v19
	v_cvt_pk_bf16_f32 v19, v20, v21
	v_lshl_add_u64 v[20:21], v[24:25], 0, v[74:75]
	global_store_dwordx2 v[20:21], v[18:19], off
	s_waitcnt vmcnt(4)
	v_lshl_add_u64 v[18:19], s[0:1], 0, v[82:83]
	s_barrier
	global_load_dwordx2 v[228:229], v[70:71], off offset:256
	global_load_dwordx2 v[230:231], v[70:71], off offset:288
	global_load_dwordx2 v[232:233], v[70:71], off offset:320
	global_load_dwordx2 v[234:235], v[70:71], off offset:352
	v_lshl_add_u64 v[18:19], v[18:19], 0, v[0:1]
	global_load_lds_dwordx4 v[18:19], off
	v_lshl_add_u64 v[18:19], s[6:7], 0, v[84:85]
	v_lshl_add_u64 v[18:19], v[18:19], 0, v[86:87]
	s_mov_b32 m0, s8
	v_readfirstlane_b32 s8, v120
	global_load_lds_dwordx4 v[18:19], off
	v_lshl_add_u64 v[18:19], s[0:1], 0, v[88:89]
	v_lshl_add_u64 v[18:19], v[18:19], 0, v[90:91]
	s_mov_b32 m0, s8
	v_readfirstlane_b32 s8, v121
	global_load_lds_dwordx4 v[18:19], off
	v_lshl_add_u64 v[18:19], s[6:7], 0, v[92:93]
	v_lshl_add_u64 v[18:19], v[18:19], 0, v[94:95]
	s_mov_b32 m0, s8
	v_readfirstlane_b32 s8, v122
	global_load_lds_dwordx4 v[18:19], off
	v_lshl_add_u64 v[18:19], s[0:1], 0, v[96:97]
	v_lshl_add_u64 v[18:19], v[18:19], 0, v[98:99]
	s_mov_b32 m0, s8
	v_readfirstlane_b32 s8, v123
	global_load_lds_dwordx4 v[18:19], off
	v_lshl_add_u64 v[18:19], s[6:7], 0, v[100:101]
	v_lshl_add_u64 v[18:19], v[18:19], 0, v[102:103]
	s_mov_b32 m0, s8
	s_nop 0
	global_load_lds_dwordx4 v[18:19], off
	v_lshl_add_u64 v[18:19], s[0:1], 0, v[104:105]
	v_readfirstlane_b32 s0, v124
	v_lshl_add_u64 v[18:19], v[18:19], 0, v[106:107]
	s_mov_b32 m0, s0
	v_readfirstlane_b32 s0, v125
	global_load_lds_dwordx4 v[18:19], off
	v_lshl_add_u64 v[18:19], s[6:7], 0, v[108:109]
	v_lshl_add_u64 v[18:19], v[18:19], 0, v[110:111]
	s_mov_b32 m0, s0
	s_nop 0
	global_load_lds_dwordx4 v[18:19], off
	ds_read_b128 v[42:45], v117 offset:12288
	ds_read_b128 v[46:49], v117 offset:14336
	s_waitcnt lgkmcnt(0)
	v_mfma_f32_16x16x32_bf16 v[82:85], v[46:49], v[14:17], 0
	ds_read_b128 v[46:49], v117 offset:16384
	ds_read_b128 v[18:21], v117
	ds_read_b128 v[22:25], v117 offset:2048
	s_waitcnt lgkmcnt(0)
	v_mfma_f32_16x16x32_bf16 v[86:89], v[46:49], v[14:17], 0
	ds_read_b128 v[46:49], v117 offset:18432
	ds_read_b128 v[26:29], v117 offset:4096
	ds_read_b128 v[30:33], v117 offset:6144
	s_waitcnt lgkmcnt(0)
	v_mfma_f32_16x16x32_bf16 v[90:93], v[46:49], v[14:17], 0
	ds_read_b128 v[46:49], v117 offset:20480
	ds_read_b128 v[34:37], v117 offset:8192
	ds_read_b128 v[38:41], v117 offset:10240
	s_waitcnt lgkmcnt(0)
	v_mfma_f32_16x16x32_bf16 v[94:97], v[46:49], v[14:17], 0
	ds_read_b128 v[46:49], v117 offset:22528
	s_waitcnt lgkmcnt(0)
; DI f32x4 mfma16(bf16x8 a, bf16x8 b, f32x4 c) { return __builtin_amdgcn_mfma_f32_16x16x32_bf16(a, b, c, 0, 0, 0); }
; DI void unit_X(const Params& p, char* lds, int l, int chunk) {
;     ...
;         f32x4 s[16];
; #pragma unroll
;         for (int mt = 0; mt < 16; ++mt) s[mt] = (f32x4){0.f, 0.f, 0.f, 0.f};
; #pragma unroll
;         for (int ks = 0; ks < 2; ++ks) {
; #pragma unroll
;             for (int mt = 0; mt < 16; ++mt) {
;                 const int row = 16 * mt + l15;
;                 const bf16x8 ak = *(const bf16x8*)(kd + row * 128 + (((4 * ks + quad) ^ ((row >> 1) & 7)) << 4));
;                 s[mt] = mfma16(ak, bq[h][ks], s[mt]);
;             }
;         }
;         float mxv = -3.0e38f;
; #pragma unroll
;         for (int mt = 0; mt < 16; ++mt)
; #pragma unroll
;             for (int i = 0; i < 4; ++i) mxv = fmaxf(mxv, s[mt][i]);
;         mxv = fmaxf(mxv, __shfl_xor(mxv, 16));
	v_mfma_f32_16x16x32_bf16 v[98:101], v[46:49], v[14:17], 0
	ds_read_b128 v[46:49], v117 offset:24576
	s_waitcnt lgkmcnt(0)
	v_mfma_f32_16x16x32_bf16 v[102:105], v[46:49], v[14:17], 0
	ds_read_b128 v[46:49], v117 offset:26624
	s_waitcnt lgkmcnt(0)
	v_mfma_f32_16x16x32_bf16 v[106:109], v[46:49], v[14:17], 0
	ds_read_b128 v[46:49], v117 offset:28672
	s_waitcnt lgkmcnt(0)
	v_mfma_f32_16x16x32_bf16 v[118:121], v[46:49], v[14:17], 0
	ds_read_b128 v[46:49], v117 offset:30720
	v_mfma_f32_16x16x32_bf16 v[18:21], v[18:21], v[14:17], 0
	v_mfma_f32_16x16x32_bf16 v[22:25], v[22:25], v[14:17], 0
	v_mfma_f32_16x16x32_bf16 v[26:29], v[26:29], v[14:17], 0
	v_mfma_f32_16x16x32_bf16 v[30:33], v[30:33], v[14:17], 0
	v_mfma_f32_16x16x32_bf16 v[34:37], v[34:37], v[14:17], 0
	v_mfma_f32_16x16x32_bf16 v[38:41], v[38:41], v[14:17], 0
	v_mfma_f32_16x16x32_bf16 v[42:45], v[42:45], v[14:17], 0
	s_waitcnt lgkmcnt(0)
	v_mfma_f32_16x16x32_bf16 v[122:125], v[46:49], v[14:17], 0
	ds_read_b128 v[14:17], v116
	s_waitcnt lgkmcnt(0)
	v_mfma_f32_16x16x32_bf16 v[130:133], v[14:17], v[10:13], v[18:21]
	ds_read_b128 v[14:17], v116 offset:2048
	s_nop 6
	v_max3_f32 v0, v130, s13, v131
	s_waitcnt lgkmcnt(0)
	v_mfma_f32_16x16x32_bf16 v[134:137], v[14:17], v[10:13], v[22:25]
	ds_read_b128 v[14:17], v116 offset:4096
	v_max3_f32 v0, v0, v132, v133
	s_nop 5
	v_max3_f32 v0, v0, v134, v135
	s_waitcnt lgkmcnt(0)
	v_mfma_f32_16x16x32_bf16 v[138:141], v[14:17], v[10:13], v[26:29]
	ds_read_b128 v[14:17], v116 offset:6144
	v_max3_f32 v0, v0, v136, v137
	s_nop 5
	v_max3_f32 v0, v0, v138, v139
	s_waitcnt lgkmcnt(0)
	v_mfma_f32_16x16x32_bf16 v[58:61], v[14:17], v[10:13], v[30:33]
	ds_read_b128 v[14:17], v116 offset:8192
	v_max3_f32 v0, v0, v140, v141
	s_nop 5
	v_max3_f32 v0, v0, v58, v59
	s_waitcnt lgkmcnt(0)
	v_mfma_f32_16x16x32_bf16 v[54:57], v[14:17], v[10:13], v[34:37]
	ds_read_b128 v[14:17], v116 offset:10240
	v_max3_f32 v0, v0, v60, v61
	s_nop 5
	v_max3_f32 v0, v0, v54, v55
	s_waitcnt lgkmcnt(0)
	v_mfma_f32_16x16x32_bf16 v[50:53], v[14:17], v[10:13], v[38:41]
	ds_read_b128 v[14:17], v116 offset:12288
	v_max3_f32 v0, v0, v56, v57
	s_nop 5
	v_max3_f32 v0, v0, v50, v51
	s_waitcnt lgkmcnt(0)
	v_mfma_f32_16x16x32_bf16 v[46:49], v[14:17], v[10:13], v[42:45]
	ds_read_b128 v[14:17], v116 offset:14336
	v_max3_f32 v0, v0, v52, v53
	s_nop 5
	v_max3_f32 v0, v0, v46, v47
	s_waitcnt lgkmcnt(0)
	v_mfma_f32_16x16x32_bf16 v[42:45], v[14:17], v[10:13], v[82:85]
	ds_read_b128 v[14:17], v116 offset:16384
	s_nop 1
	ds_read_b128 v[82:85], v116 offset:30720
	v_max3_f32 v0, v0, v48, v49
	s_waitcnt lgkmcnt(0)
	v_mfma_f32_16x16x32_bf16 v[38:41], v[14:17], v[10:13], v[86:89]
	ds_read_b128 v[14:17], v116 offset:18432
	v_max3_f32 v0, v0, v42, v43
	v_max3_f32 v0, v0, v44, v45
	s_waitcnt lgkmcnt(0)
	v_mfma_f32_16x16x32_bf16 v[34:37], v[14:17], v[10:13], v[90:93]
	ds_read_b128 v[14:17], v116 offset:20480
	s_nop 1
	v_max3_f32 v0, v0, v38, v39
	v_max3_f32 v0, v0, v40, v41
	s_waitcnt lgkmcnt(0)
	v_mfma_f32_16x16x32_bf16 v[30:33], v[14:17], v[10:13], v[94:97]
	ds_read_b128 v[14:17], v116 offset:22528
	v_max3_f32 v0, v0, v34, v35
	v_max3_f32 v0, v0, v36, v37
	s_waitcnt lgkmcnt(0)
	v_mfma_f32_16x16x32_bf16 v[26:29], v[14:17], v[10:13], v[98:101]
	ds_read_b128 v[14:17], v116 offset:24576
	s_nop 1
	v_max3_f32 v0, v0, v30, v31
	v_max3_f32 v0, v0, v32, v33
	s_waitcnt lgkmcnt(0)
	v_mfma_f32_16x16x32_bf16 v[22:25], v[14:17], v[10:13], v[102:105]
	ds_read_b128 v[14:17], v116 offset:26624
	v_max3_f32 v0, v0, v26, v27
	v_max3_f32 v0, v0, v28, v29
	s_waitcnt lgkmcnt(0)
	v_mfma_f32_16x16x32_bf16 v[18:21], v[14:17], v[10:13], v[106:109]
	ds_read_b128 v[14:17], v116 offset:28672
	s_nop 1
	v_max3_f32 v0, v0, v22, v23
	v_max3_f32 v0, v0, v24, v25
	s_waitcnt lgkmcnt(0)
	v_mfma_f32_16x16x32_bf16 v[14:17], v[14:17], v[10:13], v[118:121]
	s_nop 0
	v_max3_f32 v0, v0, v18, v19
	v_max3_f32 v0, v0, v20, v21
	ds_read_b128 v[98:101], v79 offset:49152
	v_mfma_f32_16x16x32_bf16 v[10:13], v[82:85], v[10:13], v[122:125]
	s_nop 2
	v_max3_f32 v0, v0, v14, v15
	v_max3_f32 v0, v0, v16, v17
	ds_read_b128 v[102:105], v79 offset:57344
	s_nop 1
	v_max3_f32 v0, v0, v10, v11
	v_max3_f32 v0, v0, v12, v13
	ds_bpermute_b32 v82, v114, v0
	s_waitcnt lgkmcnt(0)
	v_max_f32_e32 v82, v82, v82
	v_max_f32_e32 v0, v0, v82
	ds_bpermute_b32 v82, v115, v0
	s_waitcnt lgkmcnt(0)
; DI unsigned pk2(float lo, float hi) { const f32x2 v = {lo, hi}; const bf16x2_t b = __builtin_convertvector(v, bf16x2_t); return __builtin_bit_cast(unsigned, b); }
; DI void unit_X(const Params& p, char* lds, int l, int chunk) {
;     ...
;         float sum = 0.f;
; #pragma unroll
;         for (int mt = 0; mt < 16; ++mt)
; #pragma unroll
;             for (int i = 0; i < 4; ++i) { const float e = __builtin_amdgcn_exp2f(s[mt][i] - mxv); s[mt][i] = e; sum += e; }
;         sum += __shfl_xor(sum, 16);
;         sum += __shfl_xor(sum, 32);
;         const float inv = 1.f / sum;
;         f32x4 o[4];
; #pragma unroll
;         for (int dt = 0; dt < 4; ++dt) o[dt] = (f32x4){0.f, 0.f, 0.f, 0.f};
; #pragma unroll
;         for (int ks = 0; ks < 8; ++ks) {
;             const f32x4 a = s[2 * ks], c = s[2 * ks + 1];
;             const u32x4 w = (u32x4){pk2(a[0], a[1]), pk2(a[2], a[3]), pk2(c[0], c[1]), pk2(c[2], c[3])};
;             const bf16x8 pb = __builtin_bit_cast(bf16x8, w);
	v_max_f32_e32 v82, v82, v82
	v_max_f32_e32 v89, v0, v82
	v_sub_f32_e32 v0, v130, v89
	v_exp_f32_e32 v90, v0
	v_sub_f32_e32 v82, v131, v89
	v_exp_f32_e32 v91, v82
	v_sub_f32_e32 v82, v132, v89
	v_exp_f32_e32 v92, v82
	v_sub_f32_e32 v82, v133, v89
	v_exp_f32_e32 v93, v82
	v_sub_f32_e32 v82, v134, v89
	v_add_f32_e32 v0, 0, v90
	v_exp_f32_e32 v94, v82
	v_sub_f32_e32 v82, v135, v89
	v_add_f32_e32 v0, v91, v0
	v_exp_f32_e32 v95, v82
	v_sub_f32_e32 v82, v136, v89
	v_add_f32_e32 v0, v92, v0
	v_exp_f32_e32 v96, v82
	v_sub_f32_e32 v82, v137, v89
	v_add_f32_e32 v0, v93, v0
	v_exp_f32_e32 v97, v82
	v_sub_f32_e32 v82, v138, v89
	v_add_f32_e32 v0, v94, v0
	v_exp_f32_e32 v82, v82
	v_sub_f32_e32 v83, v139, v89
	v_add_f32_e32 v0, v95, v0
	v_exp_f32_e32 v83, v83
	v_sub_f32_e32 v84, v140, v89
	v_add_f32_e32 v0, v96, v0
	v_exp_f32_e32 v84, v84
	v_sub_f32_e32 v85, v141, v89
	v_add_f32_e32 v0, v97, v0
	v_exp_f32_e32 v85, v85
	v_sub_f32_e32 v58, v58, v89
	v_add_f32_e32 v0, v82, v0
	v_exp_f32_e32 v58, v58
	v_sub_f32_e32 v59, v59, v89
	v_add_f32_e32 v0, v83, v0
	v_exp_f32_e32 v59, v59
	v_sub_f32_e32 v60, v60, v89
	v_add_f32_e32 v0, v84, v0
	v_exp_f32_e32 v60, v60
	v_sub_f32_e32 v61, v61, v89
	v_add_f32_e32 v0, v85, v0
	v_exp_f32_e32 v61, v61
	v_sub_f32_e32 v54, v54, v89
	v_add_f32_e32 v0, v58, v0
	v_exp_f32_e32 v54, v54
	v_sub_f32_e32 v55, v55, v89
	v_add_f32_e32 v0, v59, v0
	v_exp_f32_e32 v55, v55
	v_sub_f32_e32 v56, v56, v89
	v_add_f32_e32 v0, v60, v0
	v_exp_f32_e32 v56, v56
	v_sub_f32_e32 v57, v57, v89
	v_add_f32_e32 v0, v61, v0
	v_exp_f32_e32 v57, v57
	v_sub_f32_e32 v50, v50, v89
	v_add_f32_e32 v0, v54, v0
	v_exp_f32_e32 v50, v50
	v_sub_f32_e32 v51, v51, v89
	v_add_f32_e32 v0, v55, v0
	v_exp_f32_e32 v51, v51
	v_sub_f32_e32 v52, v52, v89
	v_add_f32_e32 v0, v56, v0
	v_exp_f32_e32 v52, v52
	v_sub_f32_e32 v53, v53, v89
	v_add_f32_e32 v0, v57, v0
	v_exp_f32_e32 v53, v53
	v_add_f32_e32 v0, v50, v0
	v_add_f32_e32 v0, v51, v0
	v_add_f32_e32 v0, v52, v0
	v_add_f32_e32 v86, v53, v0
	v_sub_f32_e32 v0, v46, v89
	v_exp_f32_e32 v0, v0
	v_sub_f32_e32 v46, v47, v89
	v_exp_f32_e32 v46, v46
	v_sub_f32_e32 v47, v48, v89
	v_exp_f32_e32 v47, v47
	v_sub_f32_e32 v48, v49, v89
	v_exp_f32_e32 v48, v48
	v_sub_f32_e32 v42, v42, v89
	v_add_f32_e32 v86, v0, v86
	v_exp_f32_e32 v42, v42
	v_sub_f32_e32 v43, v43, v89
	v_add_f32_e32 v86, v46, v86
	v_exp_f32_e32 v43, v43
	v_sub_f32_e32 v44, v44, v89
	v_add_f32_e32 v86, v47, v86
	v_exp_f32_e32 v44, v44
	v_sub_f32_e32 v45, v45, v89
	v_add_f32_e32 v49, v48, v86
	v_exp_f32_e32 v45, v45
	v_sub_f32_e32 v38, v38, v89
	v_add_f32_e32 v49, v42, v49
	v_exp_f32_e32 v38, v38
	v_sub_f32_e32 v39, v39, v89
	v_add_f32_e32 v49, v43, v49
	v_exp_f32_e32 v39, v39
	v_sub_f32_e32 v40, v40, v89
	v_add_f32_e32 v49, v44, v49
	v_exp_f32_e32 v40, v40
	v_sub_f32_e32 v41, v41, v89
	v_add_f32_e32 v49, v45, v49
	v_exp_f32_e32 v41, v41
	v_sub_f32_e32 v34, v34, v89
	v_add_f32_e32 v49, v38, v49
	v_exp_f32_e32 v34, v34
	v_sub_f32_e32 v35, v35, v89
	v_add_f32_e32 v49, v39, v49
	v_exp_f32_e32 v35, v35
	v_sub_f32_e32 v36, v36, v89
	v_add_f32_e32 v49, v40, v49
	v_exp_f32_e32 v36, v36
	v_sub_f32_e32 v37, v37, v89
	v_add_f32_e32 v49, v41, v49
	v_exp_f32_e32 v37, v37
	v_sub_f32_e32 v30, v30, v89
	v_add_f32_e32 v49, v34, v49
	v_exp_f32_e32 v30, v30
	v_sub_f32_e32 v31, v31, v89
	v_add_f32_e32 v49, v35, v49
	v_exp_f32_e32 v31, v31
	v_sub_f32_e32 v32, v32, v89
	v_add_f32_e32 v49, v36, v49
	v_exp_f32_e32 v32, v32
	v_sub_f32_e32 v33, v33, v89
	v_add_f32_e32 v49, v37, v49
	v_exp_f32_e32 v33, v33
	v_sub_f32_e32 v26, v26, v89
	v_add_f32_e32 v49, v30, v49
	v_exp_f32_e32 v26, v26
	v_sub_f32_e32 v27, v27, v89
	v_add_f32_e32 v49, v31, v49
	v_exp_f32_e32 v27, v27
	v_sub_f32_e32 v28, v28, v89
	v_add_f32_e32 v49, v32, v49
	v_exp_f32_e32 v28, v28
	v_sub_f32_e32 v29, v29, v89
	v_add_f32_e32 v49, v33, v49
	v_exp_f32_e32 v29, v29
	v_sub_f32_e32 v22, v22, v89
	v_add_f32_e32 v49, v26, v49
	v_exp_f32_e32 v22, v22
	v_sub_f32_e32 v23, v23, v89
	v_add_f32_e32 v49, v27, v49
	v_exp_f32_e32 v23, v23
	v_sub_f32_e32 v24, v24, v89
	v_add_f32_e32 v49, v28, v49
	v_exp_f32_e32 v24, v24
	v_sub_f32_e32 v25, v25, v89
	v_add_f32_e32 v49, v29, v49
	v_exp_f32_e32 v25, v25
	v_sub_f32_e32 v18, v18, v89
	v_add_f32_e32 v49, v22, v49
	v_exp_f32_e32 v18, v18
	v_sub_f32_e32 v19, v19, v89
	v_add_f32_e32 v49, v23, v49
	v_exp_f32_e32 v19, v19
	v_sub_f32_e32 v20, v20, v89
	v_add_f32_e32 v49, v24, v49
	v_exp_f32_e32 v20, v20
	v_sub_f32_e32 v21, v21, v89
	v_add_f32_e32 v49, v25, v49
	v_exp_f32_e32 v21, v21
	v_sub_f32_e32 v14, v14, v89
	v_add_f32_e32 v49, v18, v49
	v_exp_f32_e32 v14, v14
	v_sub_f32_e32 v15, v15, v89
	v_add_f32_e32 v49, v19, v49
	v_exp_f32_e32 v15, v15
	v_sub_f32_e32 v16, v16, v89
	v_add_f32_e32 v49, v20, v49
	v_exp_f32_e32 v16, v16
	v_sub_f32_e32 v17, v17, v89
	v_add_f32_e32 v49, v21, v49
	v_exp_f32_e32 v17, v17
	v_sub_f32_e32 v10, v10, v89
	v_add_f32_e32 v49, v14, v49
	v_exp_f32_e32 v86, v10
	v_sub_f32_e32 v11, v11, v89
	v_add_f32_e32 v49, v15, v49
	v_exp_f32_e32 v87, v11
	v_sub_f32_e32 v11, v12, v89
	v_add_f32_e32 v49, v16, v49
	v_exp_f32_e32 v88, v11
	v_sub_f32_e32 v11, v13, v89
	v_add_f32_e32 v49, v17, v49
	v_exp_f32_e32 v89, v11
	v_add_f32_e32 v10, v86, v49
	v_add_f32_e32 v10, v87, v10
	v_add_f32_e32 v10, v88, v10
	v_add_f32_e32 v10, v89, v10
	ds_bpermute_b32 v11, v114, v10
	v_cvt_pk_bf16_f32 v82, v82, v83
	v_cvt_pk_bf16_f32 v83, v84, v85
	v_cvt_pk_bf16_f32 v84, v58, v59
	v_cvt_pk_bf16_f32 v85, v60, v61
	s_waitcnt lgkmcnt(0)
	v_add_f32_e32 v10, v10, v11
	ds_bpermute_b32 v11, v115, v10
	ds_read_b128 v[58:61], v78 offset:32768
	v_cvt_pk_bf16_f32 v12, v94, v95
	v_cvt_pk_bf16_f32 v13, v96, v97
	ds_read_b128 v[94:97], v79 offset:40960
	s_waitcnt lgkmcnt(0)
; DI unsigned pk2(float lo, float hi) { const f32x2 v = {lo, hi}; const bf16x2_t b = __builtin_convertvector(v, bf16x2_t); return __builtin_bit_cast(unsigned, b); }
; DI float bf2f(unsigned b) { return __uint_as_float(b << 16); }
; DI f32x4 mfma16(bf16x8 a, bf16x8 b, f32x4 c) { return __builtin_amdgcn_mfma_f32_16x16x32_bf16(a, b, c, 0, 0, 0); }
; DI void unit_X(const Params& p, char* lds, int l, int chunk) {
;     ...
;         for (int ks = 0; ks < 8; ++ks) {
;             const f32x4 a = s[2 * ks], c = s[2 * ks + 1];
;             const u32x4 w = (u32x4){pk2(a[0], a[1]), pk2(a[2], a[3]), pk2(c[0], c[1]), pk2(c[2], c[3])};
;             const bf16x8 pb = __builtin_bit_cast(bf16x8, w);
; #pragma unroll
;             for (int dt = 0; dt < 4; ++dt) {
;                 const int row = 16 * dt + l15;
;                 const bf16x8 av = *(const bf16x8*)(vd + row * 512 + (((4 * ks + quad) ^ (row & 15)) << 4));
;                 o[dt] = mfma16(av, pb, o[dt]);
;             }
;         }
; #pragma unroll
;         for (int dt = 0; dt < 4; ++dt) {
;             const int d = 16 * dt + 4 * quad;
;             const u32x2 gv = *(const u32x2*)(gx + (size_t)tok * 256 + 64 * h + d);
;             const float o0 = o[dt][0] * inv * bf2f(gv[0] & 0xffffu), o1 = o[dt][1] * inv * bf2f(gv[0] >> 16);
;             const float o2 = o[dt][2] * inv * bf2f(gv[1] & 0xffffu), o3 = o[dt][3] * inv * bf2f(gv[1] >> 16);
	v_add_f32_e32 v49, v10, v11
	v_cvt_pk_bf16_f32 v10, v90, v91
	v_cvt_pk_bf16_f32 v11, v92, v93
	ds_read_b128 v[90:93], v79 offset:32768
	v_cvt_pk_bf16_f32 v54, v54, v55
	s_waitcnt lgkmcnt(0)
	v_mfma_f32_16x16x32_bf16 v[90:93], v[90:93], v[10:13], 0
	v_cvt_pk_bf16_f32 v55, v56, v57
	v_cvt_pk_bf16_f32 v56, v50, v51
	v_cvt_pk_bf16_f32 v57, v52, v53
	v_mfma_f32_16x16x32_bf16 v[58:61], v[58:61], v[82:85], v[90:93]
	ds_read_b128 v[50:53], v77 offset:32768
	v_cvt_pk_bf16_f32 v38, v38, v39
	v_cvt_pk_bf16_f32 v39, v40, v41
	s_nop 0
	ds_read_b128 v[90:93], v78 offset:40960
	v_mfma_f32_16x16x32_bf16 v[94:97], v[94:97], v[10:13], 0
	v_cvt_pk_bf16_f32 v40, v34, v35
	v_cvt_pk_bf16_f32 v41, v36, v37
	ds_read_b128 v[34:37], v126 offset:32768
	s_waitcnt lgkmcnt(0)
	v_mfma_f32_16x16x32_bf16 v[90:93], v[90:93], v[82:85], v[94:97]
	s_nop 2
	ds_read_b128 v[94:97], v78 offset:49152
	v_cvt_pk_bf16_f32 v30, v30, v31
	v_cvt_pk_bf16_f32 v31, v32, v33
	v_mfma_f32_16x16x32_bf16 v[98:101], v[98:101], v[10:13], 0
	v_cvt_pk_bf16_f32 v32, v26, v27
	v_cvt_pk_bf16_f32 v33, v28, v29
	ds_read_b128 v[26:29], v127 offset:32768
	s_waitcnt lgkmcnt(0)
	v_mfma_f32_16x16x32_bf16 v[94:97], v[94:97], v[82:85], v[98:101]
	v_cvt_pk_bf16_f32 v22, v22, v23
	s_nop 1
	ds_read_b128 v[98:101], v78 offset:57344
	v_cvt_pk_bf16_f32 v23, v24, v25
	v_mfma_f32_16x16x32_bf16 v[10:13], v[102:105], v[10:13], 0
	v_cvt_pk_bf16_f32 v24, v18, v19
	v_cvt_pk_bf16_f32 v25, v20, v21
	ds_read_b128 v[18:21], v128 offset:32768
	s_waitcnt lgkmcnt(0)
	v_mfma_f32_16x16x32_bf16 v[10:13], v[98:101], v[82:85], v[10:13]
	ds_read_b128 v[82:85], v77 offset:49152
	v_mfma_f32_16x16x32_bf16 v[50:53], v[50:53], v[54:57], v[58:61]
	s_nop 2
	ds_read_b128 v[58:61], v77 offset:40960
	s_waitcnt lgkmcnt(0)
	v_mfma_f32_16x16x32_bf16 v[58:61], v[58:61], v[54:57], v[90:93]
	s_nop 2
	ds_read_b128 v[90:93], v77 offset:57344
	v_mfma_f32_16x16x32_bf16 v[82:85], v[82:85], v[54:57], v[94:97]
	s_waitcnt lgkmcnt(0)
	v_mfma_f32_16x16x32_bf16 v[10:13], v[90:93], v[54:57], v[10:13]
	v_cvt_pk_bf16_f32 v56, v42, v43
	v_cvt_pk_bf16_f32 v57, v44, v45
	ds_read_b128 v[42:45], v81 offset:32768
	v_cvt_pk_bf16_f32 v54, v0, v46
	v_cvt_pk_bf16_f32 v55, v47, v48
	v_div_scale_f32 v0, s[0:1], v49, v49, 1.0
	s_waitcnt lgkmcnt(0)
	v_mfma_f32_16x16x32_bf16 v[42:45], v[42:45], v[54:57], v[50:53]
	s_nop 2
	ds_read_b128 v[50:53], v81 offset:40960
	v_mfma_f32_16x16x32_bf16 v[34:37], v[34:37], v[38:41], v[42:45]
	s_nop 2
	ds_read_b128 v[42:45], v126 offset:40960
	s_waitcnt lgkmcnt(0)
	v_mfma_f32_16x16x32_bf16 v[50:53], v[50:53], v[54:57], v[58:61]
	s_nop 2
	ds_read_b128 v[58:61], v81 offset:49152
	v_mfma_f32_16x16x32_bf16 v[42:45], v[42:45], v[38:41], v[50:53]
	s_nop 2
	ds_read_b128 v[50:53], v126 offset:49152
	s_waitcnt lgkmcnt(0)
	v_mfma_f32_16x16x32_bf16 v[58:61], v[58:61], v[54:57], v[82:85]
	s_nop 2
	ds_read_b128 v[82:85], v81 offset:57344
	v_mfma_f32_16x16x32_bf16 v[26:29], v[26:29], v[30:33], v[34:37]
	s_nop 2
	ds_read_b128 v[34:37], v127 offset:40960
	s_waitcnt lgkmcnt(0)
	v_mfma_f32_16x16x32_bf16 v[10:13], v[82:85], v[54:57], v[10:13]
	ds_read_b128 v[54:57], v126 offset:57344
	v_mfma_f32_16x16x32_bf16 v[50:53], v[50:53], v[38:41], v[58:61]
	v_mfma_f32_16x16x32_bf16 v[34:37], v[34:37], v[30:33], v[42:45]
	s_nop 2
	ds_read_b128 v[42:45], v127 offset:57344
	s_waitcnt lgkmcnt(0)
	v_mfma_f32_16x16x32_bf16 v[10:13], v[54:57], v[38:41], v[10:13]
	ds_read_b128 v[38:41], v127 offset:49152
	v_mfma_f32_16x16x32_bf16 v[18:21], v[18:21], v[22:25], v[26:29]
	s_nop 2
	ds_read_b128 v[26:29], v128 offset:40960
	s_waitcnt lgkmcnt(0)
	v_mfma_f32_16x16x32_bf16 v[38:41], v[38:41], v[30:33], v[50:53]
	v_mfma_f32_16x16x32_bf16 v[10:13], v[42:45], v[30:33], v[10:13]
	ds_read_b128 v[30:33], v128 offset:49152
	v_mfma_f32_16x16x32_bf16 v[26:29], v[26:29], v[22:25], v[34:37]
	s_nop 2
	ds_read_b128 v[34:37], v128 offset:57344
	s_waitcnt lgkmcnt(0)
	v_mfma_f32_16x16x32_bf16 v[10:13], v[34:37], v[22:25], v[10:13]
	v_cvt_pk_bf16_f32 v34, v14, v15
	v_cvt_pk_bf16_f32 v35, v16, v17
	ds_read_b128 v[14:17], v129 offset:32768
	v_cvt_pk_bf16_f32 v36, v86, v87
	v_cvt_pk_bf16_f32 v37, v88, v89
	v_mfma_f32_16x16x32_bf16 v[30:33], v[30:33], v[22:25], v[38:41]
	s_waitcnt lgkmcnt(0)
	v_mfma_f32_16x16x32_bf16 v[22:25], v[14:17], v[34:37], v[18:21]
	ds_read_b128 v[14:17], v129 offset:40960
	s_waitcnt lgkmcnt(0)
	v_mfma_f32_16x16x32_bf16 v[18:21], v[14:17], v[34:37], v[26:29]
	ds_read_b128 v[14:17], v129 offset:49152
	s_nop 1
	ds_read_b128 v[26:29], v129 offset:57344
	s_waitcnt lgkmcnt(0)
	v_mfma_f32_16x16x32_bf16 v[10:13], v[26:29], v[34:37], v[10:13]
	v_rcp_f32_e32 v26, v0
	s_nop 0
	v_fma_f32 v27, -v0, v26, 1.0
	v_fmac_f32_e32 v26, v27, v26
	v_div_scale_f32 v27, vcc, 1.0, v49, 1.0
	v_mul_f32_e32 v28, v27, v26
	v_fma_f32 v29, -v0, v28, v27
	v_fmac_f32_e32 v28, v29, v26
	v_fma_f32 v0, -v0, v28, v27
	v_div_fmas_f32 v0, v0, v26, v28
	v_div_fixup_f32 v0, v0, v49, 1.0
	v_pk_mul_f32 v[22:23], v[22:23], v[0:1] op_sel_hi:[1,0]
	v_pk_mul_f32 v[24:25], v[24:25], v[0:1] op_sel_hi:[1,0]
	v_pk_mul_f32 v[18:19], v[18:19], v[0:1] op_sel_hi:[1,0]
	v_pk_mul_f32 v[20:21], v[20:21], v[0:1] op_sel_hi:[1,0]
	v_mfma_f32_16x16x32_bf16 v[14:17], v[14:17], v[34:37], v[30:33]
	v_mul_f32_e64 v10, v10, v0
	v_mul_f32_e64 v11, v11, v0
	v_pk_mul_f32 v[12:13], v[12:13], v[0:1] op_sel_hi:[1,0]
	s_waitcnt vmcnt(0)
; DI unsigned pk2(float lo, float hi) { const f32x2 v = {lo, hi}; const bf16x2_t b = __builtin_convertvector(v, bf16x2_t); return __builtin_bit_cast(unsigned, b); }
; DI float bf2f(unsigned b) { return __uint_as_float(b << 16); }
; DI f32x4 mfma16(bf16x8 a, bf16x8 b, f32x4 c) { return __builtin_amdgcn_mfma_f32_16x16x32_bf16(a, b, c, 0, 0, 0); }
; template <int N> DI void wait_vm() { asm volatile("s_waitcnt vmcnt(%0)" ::"n"(N) : "memory"); }
; DI void raw_barrier() { asm volatile("" ::: "memory"); __builtin_amdgcn_s_barrier(); asm volatile("" ::: "memory"); }
; DI size_t y_off(int tok, int col) { return ((size_t)(((tok >> 6) * 32 + (col >> 5)) * 64 + (tok & 63))) * 32 + (col & 31); }
; DI void unit_X(const Params& p, char* lds, int l, int chunk) {
;     ...
;         wait_vm<0>();
;         raw_barrier();
;         if (h < 3) issue_kv(h + 1, (h + 1) & 1);
;         const char* kd = lds + (h & 1) * 65536;
;         const char* vd = kd + 32768;
;         f32x4 s[16];
; #pragma unroll
;         for (int mt = 0; mt < 16; ++mt) s[mt] = (f32x4){0.f, 0.f, 0.f, 0.f};
; #pragma unroll
;         for (int ks = 0; ks < 2; ++ks) {
; #pragma unroll
;             for (int mt = 0; mt < 16; ++mt) {
;                 const int row = 16 * mt + l15;
;                 const bf16x8 ak = *(const bf16x8*)(kd + row * 128 + (((4 * ks + quad) ^ ((row >> 1) & 7)) << 4));
;                 s[mt] = mfma16(ak, bq[h][ks], s[mt]);
;             }
;         }
;         float mxv = -3.0e38f;
; #pragma unroll
;         for (int mt = 0; mt < 16; ++mt)
; #pragma unroll
;             for (int i = 0; i < 4; ++i) mxv = fmaxf(mxv, s[mt][i]);
;         mxv = fmaxf(mxv, __shfl_xor(mxv, 16));
;     ...
; #pragma unroll
;         for (int dt = 0; dt < 4; ++dt) {
;             const int d = 16 * dt + 4 * quad;
;             const u32x2 gv = *(const u32x2*)(gx + (size_t)tok * 256 + 64 * h + d);
;             const float o0 = o[dt][0] * inv * bf2f(gv[0] & 0xffffu), o1 = o[dt][1] * inv * bf2f(gv[0] >> 16);
;             const float o2 = o[dt][2] * inv * bf2f(gv[1] & 0xffffu), o3 = o[dt][3] * inv * bf2f(gv[1] >> 16);
;             *(u32x2*)(yo + y_off(chunk * 128 + tok, 768 + h * 64 + d)) = (u32x2){pk2(o0, o1), pk2(o2, o3)};
;         }
	v_mov_b32_e32 v26, v228
	v_mov_b32_e32 v27, v229
	v_lshlrev_b32_e32 v28, 16, v26
	v_and_b32_e32 v29, 0xffff0000, v26
	v_lshlrev_b32_e32 v26, 16, v27
	v_and_b32_e32 v27, 0xffff0000, v27
	v_pk_mul_f32 v[22:23], v[22:23], v[28:29]
	v_pk_mul_f32 v[24:25], v[24:25], v[26:27]
	v_cvt_pk_bf16_f32 v22, v22, v23
	v_cvt_pk_bf16_f32 v23, v24, v25
	v_or_b32_e32 v24, 0x700, v76
	v_ashrrev_i32_e32 v25, 31, v24
	v_lshlrev_b64 v[24:25], 6, v[24:25]
	v_lshl_add_u64 v[24:25], s[54:55], 0, v[24:25]
	v_lshl_add_u64 v[24:25], v[24:25], 0, v[72:73]
	global_store_dwordx2 v[24:25], v[22:23], off
	v_pk_mul_f32 v[14:15], v[14:15], v[0:1] op_sel_hi:[1,0]
	v_pk_mul_f32 v[16:17], v[16:17], v[0:1] op_sel_hi:[1,0]
	s_nop 1
	v_mov_b32_e32 v22, v230
	v_mov_b32_e32 v23, v231
	v_lshlrev_b32_e32 v26, 16, v22
	v_and_b32_e32 v27, 0xffff0000, v22
	v_lshlrev_b32_e32 v22, 16, v23
	v_and_b32_e32 v23, 0xffff0000, v23
	v_pk_mul_f32 v[18:19], v[18:19], v[26:27]
	v_pk_mul_f32 v[20:21], v[20:21], v[22:23]
	v_cvt_pk_bf16_f32 v18, v18, v19
	v_cvt_pk_bf16_f32 v19, v20, v21
	global_store_dwordx2 v[24:25], v[18:19], off offset:32
	s_nop 1
	v_mov_b32_e32 v18, v232
	v_mov_b32_e32 v19, v233
	v_lshlrev_b32_e32 v20, 16, v18
	v_and_b32_e32 v21, 0xffff0000, v18
	v_lshlrev_b32_e32 v18, 16, v19
	v_and_b32_e32 v19, 0xffff0000, v19
	v_pk_mul_f32 v[14:15], v[14:15], v[20:21]
	v_pk_mul_f32 v[16:17], v[16:17], v[18:19]
	v_cvt_pk_bf16_f32 v14, v14, v15
	v_cvt_pk_bf16_f32 v15, v16, v17
	v_or_b32_e32 v16, 0x740, v76
	v_ashrrev_i32_e32 v17, 31, v16
	v_lshlrev_b64 v[16:17], 6, v[16:17]
	v_lshl_add_u64 v[16:17], s[54:55], 0, v[16:17]
	v_lshl_add_u64 v[18:19], v[16:17], 0, v[72:73]
	global_store_dwordx2 v[18:19], v[14:15], off
	s_nop 1
	v_mov_b32_e32 v14, v234
	v_mov_b32_e32 v15, v235
	v_lshlrev_b32_e32 v18, 16, v14
	v_and_b32_e32 v19, 0xffff0000, v14
	v_lshlrev_b32_e32 v14, 16, v15
	v_and_b32_e32 v15, 0xffff0000, v15
	v_pk_mul_f32 v[10:11], v[10:11], v[18:19]
	v_pk_mul_f32 v[12:13], v[12:13], v[14:15]
	v_cvt_pk_bf16_f32 v10, v10, v11
	v_cvt_pk_bf16_f32 v11, v12, v13
	v_lshl_add_u64 v[12:13], v[16:17], 0, v[74:75]
	global_store_dwordx2 v[12:13], v[10:11], off
	s_waitcnt vmcnt(4)
	s_barrier
	global_load_dwordx2 v[228:229], v[70:71], off offset:384
	global_load_dwordx2 v[230:231], v[70:71], off offset:416
	global_load_dwordx2 v[232:233], v[70:71], off offset:448
	global_load_dwordx2 v[234:235], v[70:71], off offset:480
	ds_read_b128 v[42:45], v112 offset:30720
	ds_read_b128 v[46:49], v112 offset:28672
	ds_read_b128 v[10:13], v112 offset:26624
	ds_read_b128 v[14:17], v112 offset:24576
	ds_read_b128 v[18:21], v112 offset:22528
	ds_read_b128 v[22:25], v112 offset:20480
	ds_read_b128 v[26:29], v112 offset:18432
	ds_read_b128 v[30:33], v112 offset:16384
	ds_read_b128 v[34:37], v112 offset:14336
	ds_read_b128 v[38:41], v112 offset:12288
	ds_read_b128 v[50:53], v112 offset:10240
	ds_read_b128 v[54:57], v112 offset:8192
	ds_read_b128 v[58:61], v112 offset:6144
	ds_read_b128 v[82:85], v112 offset:4096
	ds_read_b128 v[86:89], v112 offset:2048
	ds_read_b128 v[90:93], v112
	ds_read_b128 v[94:97], v80 offset:30720
	ds_read_b128 v[98:101], v80 offset:28672
	ds_read_b128 v[102:105], v80 offset:26624
	ds_read_b128 v[106:109], v80 offset:24576
	ds_read_b128 v[110:113], v80 offset:22528
	ds_read_b128 v[116:119], v80 offset:20480
	ds_read_b128 v[120:123], v80 offset:18432
	ds_read_b128 v[124:127], v80 offset:16384
	ds_read_b128 v[128:131], v80 offset:14336
	ds_read_b128 v[132:135], v80 offset:12288
	ds_read_b128 v[136:139], v80 offset:10240
	ds_read_b128 v[140:143], v80 offset:8192
	ds_read_b128 v[144:147], v80 offset:6144
	ds_read_b128 v[148:151], v80 offset:4096
	ds_read_b128 v[152:155], v80 offset:2048
	ds_read_b128 v[78:81], v80
	s_waitcnt lgkmcnt(0)
	v_mfma_f32_16x16x32_bf16 v[78:81], v[78:81], v[6:9], 0
	v_mfma_f32_16x16x32_bf16 v[152:155], v[152:155], v[6:9], 0
	v_mfma_f32_16x16x32_bf16 v[148:151], v[148:151], v[6:9], 0
	v_mfma_f32_16x16x32_bf16 v[78:81], v[90:93], v[2:5], v[78:81]
	v_mfma_f32_16x16x32_bf16 v[144:147], v[144:147], v[6:9], 0
	v_mfma_f32_16x16x32_bf16 v[86:89], v[86:89], v[2:5], v[152:155]
	s_nop 5
	v_max3_f32 v0, v78, s13, v79
	v_max3_f32 v0, v0, v80, v81
	v_mfma_f32_16x16x32_bf16 v[140:143], v[140:143], v[6:9], 0
	v_mfma_f32_16x16x32_bf16 v[82:85], v[82:85], v[2:5], v[148:151]
	v_max3_f32 v0, v0, v86, v87
	v_max3_f32 v0, v0, v88, v89
	v_mfma_f32_16x16x32_bf16 v[136:139], v[136:139], v[6:9], 0
	v_mfma_f32_16x16x32_bf16 v[90:93], v[58:61], v[2:5], v[144:147]
	s_nop 3
	v_max3_f32 v0, v0, v82, v83
	v_max3_f32 v0, v0, v84, v85
	v_mfma_f32_16x16x32_bf16 v[132:135], v[132:135], v[6:9], 0
	v_mfma_f32_16x16x32_bf16 v[54:57], v[54:57], v[2:5], v[140:143]
	v_max3_f32 v0, v0, v90, v91
	v_max3_f32 v0, v0, v92, v93
	v_mfma_f32_16x16x32_bf16 v[128:131], v[128:131], v[6:9], 0
	v_mfma_f32_16x16x32_bf16 v[50:53], v[50:53], v[2:5], v[136:139]
	s_nop 3
	v_max3_f32 v0, v0, v54, v55
	v_max3_f32 v0, v0, v56, v57
	v_mfma_f32_16x16x32_bf16 v[124:127], v[124:127], v[6:9], 0
	v_mfma_f32_16x16x32_bf16 v[38:41], v[38:41], v[2:5], v[132:135]
	v_max3_f32 v0, v0, v50, v51
	v_max3_f32 v0, v0, v52, v53
	v_mfma_f32_16x16x32_bf16 v[120:123], v[120:123], v[6:9], 0
	v_mfma_f32_16x16x32_bf16 v[34:37], v[34:37], v[2:5], v[128:131]
	s_nop 3
	v_max3_f32 v0, v0, v38, v39
	v_max3_f32 v0, v0, v40, v41
	v_mfma_f32_16x16x32_bf16 v[116:119], v[116:119], v[6:9], 0
	v_mfma_f32_16x16x32_bf16 v[30:33], v[30:33], v[2:5], v[124:127]
	v_max3_f32 v0, v0, v34, v35
	v_max3_f32 v0, v0, v36, v37
	v_mfma_f32_16x16x32_bf16 v[110:113], v[110:113], v[6:9], 0
	v_mfma_f32_16x16x32_bf16 v[26:29], v[26:29], v[2:5], v[120:123]
	s_nop 3
	v_max3_f32 v0, v0, v30, v31
	v_max3_f32 v0, v0, v32, v33
	v_mfma_f32_16x16x32_bf16 v[106:109], v[106:109], v[6:9], 0
	v_mfma_f32_16x16x32_bf16 v[22:25], v[22:25], v[2:5], v[116:119]
	v_max3_f32 v0, v0, v26, v27
	v_max3_f32 v0, v0, v28, v29
	v_mfma_f32_16x16x32_bf16 v[102:105], v[102:105], v[6:9], 0
	v_mfma_f32_16x16x32_bf16 v[18:21], v[18:21], v[2:5], v[110:113]
	s_nop 3
	v_max3_f32 v0, v0, v22, v23
	v_max3_f32 v0, v0, v24, v25
	v_mfma_f32_16x16x32_bf16 v[98:101], v[98:101], v[6:9], 0
	v_mfma_f32_16x16x32_bf16 v[14:17], v[14:17], v[2:5], v[106:109]
	v_max3_f32 v0, v0, v18, v19
	v_max3_f32 v0, v0, v20, v21
	v_mfma_f32_16x16x32_bf16 v[94:97], v[94:97], v[6:9], 0
	v_mfma_f32_16x16x32_bf16 v[10:13], v[10:13], v[2:5], v[102:105]
	s_nop 3
	v_max3_f32 v0, v0, v14, v15
	v_max3_f32 v0, v0, v16, v17
	v_mfma_f32_16x16x32_bf16 v[6:9], v[46:49], v[2:5], v[98:101]
	v_mfma_f32_16x16x32_bf16 v[2:5], v[42:45], v[2:5], v[94:97]
	v_max3_f32 v0, v0, v10, v11
	v_max3_f32 v0, v0, v12, v13
	s_nop 4
	v_max3_f32 v0, v0, v6, v7
	v_max3_f32 v0, v0, v8, v9
	v_max3_f32 v0, v0, v2, v3
	v_max3_f32 v0, v0, v4, v5
	ds_bpermute_b32 v42, v114, v0
	s_waitcnt lgkmcnt(0)
; DI void unit_X(const Params& p, char* lds, int l, int chunk) {
;     ...
;         float mxv = -3.0e38f;
; #pragma unroll
;         for (int mt = 0; mt < 16; ++mt)
; #pragma unroll
;             for (int i = 0; i < 4; ++i) mxv = fmaxf(mxv, s[mt][i]);
;         mxv = fmaxf(mxv, __shfl_xor(mxv, 16));
;         mxv = fmaxf(mxv, __shfl_xor(mxv, 32));
;         float sum = 0.f;
; #pragma unroll
;         for (int mt = 0; mt < 16; ++mt)
; #pragma unroll
;             for (int i = 0; i < 4; ++i) { const float e = __builtin_amdgcn_exp2f(s[mt][i] - mxv); s[mt][i] = e; sum += e; }
;         sum += __shfl_xor(sum, 16);
;         sum += __shfl_xor(sum, 32);
;         const float inv = 1.f / sum;
	v_max_f32_e32 v42, v42, v42
	v_max_f32_e32 v0, v0, v42
	ds_bpermute_b32 v42, v115, v0
	s_waitcnt lgkmcnt(0)
	v_max_f32_e32 v42, v42, v42
	v_max_f32_e32 v94, v0, v42
	v_sub_f32_e32 v0, v78, v94
	v_exp_f32_e32 v95, v0
	v_sub_f32_e32 v42, v79, v94
	v_exp_f32_e32 v79, v42
	v_sub_f32_e32 v42, v80, v94
	v_exp_f32_e32 v80, v42
	v_sub_f32_e32 v42, v81, v94
	v_exp_f32_e32 v81, v42
	v_sub_f32_e32 v42, v86, v94
	v_add_f32_e32 v0, 0, v95
	v_exp_f32_e32 v86, v42
	v_sub_f32_e32 v42, v87, v94
	v_add_f32_e32 v0, v79, v0
	v_exp_f32_e32 v87, v42
	v_sub_f32_e32 v42, v88, v94
	v_add_f32_e32 v0, v80, v0
	v_exp_f32_e32 v88, v42
	v_sub_f32_e32 v42, v89, v94
	v_add_f32_e32 v0, v81, v0
	v_exp_f32_e32 v89, v42
	v_sub_f32_e32 v42, v82, v94
	v_add_f32_e32 v0, v86, v0
	v_exp_f32_e32 v47, v42
	v_sub_f32_e32 v42, v83, v94
	v_add_f32_e32 v0, v87, v0
	v_exp_f32_e32 v49, v42
	v_sub_f32_e32 v42, v84, v94
	v_add_f32_e32 v0, v88, v0
	v_exp_f32_e32 v58, v42
	v_sub_f32_e32 v42, v85, v94
	v_add_f32_e32 v0, v89, v0
	v_exp_f32_e32 v59, v42
	v_sub_f32_e32 v42, v90, v94
	v_add_f32_e32 v0, v47, v0
	v_exp_f32_e32 v60, v42
	v_sub_f32_e32 v42, v91, v94
	v_add_f32_e32 v0, v49, v0
	v_exp_f32_e32 v61, v42
	v_sub_f32_e32 v42, v92, v94
	v_add_f32_e32 v0, v58, v0
	v_exp_f32_e32 v77, v42
	v_sub_f32_e32 v42, v93, v94
	v_add_f32_e32 v0, v59, v0
	v_exp_f32_e32 v78, v42
	v_sub_f32_e32 v42, v54, v94
	v_add_f32_e32 v0, v60, v0
	v_exp_f32_e32 v42, v42
	v_sub_f32_e32 v43, v55, v94
	v_add_f32_e32 v0, v61, v0
	v_exp_f32_e32 v43, v43
	v_sub_f32_e32 v44, v56, v94
	v_add_f32_e32 v0, v77, v0
	v_exp_f32_e32 v44, v44
	v_sub_f32_e32 v45, v57, v94
	v_add_f32_e32 v0, v78, v0
	v_exp_f32_e32 v45, v45
	v_sub_f32_e32 v46, v50, v94
	v_add_f32_e32 v0, v42, v0
	v_exp_f32_e32 v46, v46
	v_sub_f32_e32 v48, v51, v94
	v_add_f32_e32 v0, v43, v0
	v_exp_f32_e32 v48, v48
	v_sub_f32_e32 v50, v52, v94
	v_add_f32_e32 v0, v44, v0
	v_exp_f32_e32 v50, v50
	v_sub_f32_e32 v51, v53, v94
	v_add_f32_e32 v0, v45, v0
	v_exp_f32_e32 v51, v51
	v_add_f32_e32 v0, v46, v0
	v_add_f32_e32 v0, v48, v0
	v_add_f32_e32 v0, v50, v0
	v_add_f32_e32 v52, v51, v0
	v_sub_f32_e32 v0, v38, v94
	v_exp_f32_e32 v0, v0
	v_sub_f32_e32 v38, v39, v94
	v_exp_f32_e32 v38, v38
	v_sub_f32_e32 v39, v40, v94
	v_exp_f32_e32 v39, v39
	v_sub_f32_e32 v40, v41, v94
	v_exp_f32_e32 v40, v40
	v_sub_f32_e32 v34, v34, v94
	v_add_f32_e32 v52, v0, v52
	v_exp_f32_e32 v34, v34
	v_sub_f32_e32 v35, v35, v94
	v_add_f32_e32 v52, v38, v52
	v_exp_f32_e32 v35, v35
	v_sub_f32_e32 v36, v36, v94
	v_add_f32_e32 v52, v39, v52
	v_exp_f32_e32 v36, v36
	v_sub_f32_e32 v37, v37, v94
	v_add_f32_e32 v41, v40, v52
	v_exp_f32_e32 v37, v37
	v_sub_f32_e32 v30, v30, v94
	v_add_f32_e32 v41, v34, v41
	v_exp_f32_e32 v30, v30
	v_sub_f32_e32 v31, v31, v94
	v_add_f32_e32 v41, v35, v41
	v_exp_f32_e32 v31, v31
	v_sub_f32_e32 v32, v32, v94
	v_add_f32_e32 v41, v36, v41
	v_exp_f32_e32 v32, v32
	v_sub_f32_e32 v33, v33, v94
	v_add_f32_e32 v41, v37, v41
	v_exp_f32_e32 v33, v33
	v_sub_f32_e32 v26, v26, v94
	v_add_f32_e32 v41, v30, v41
	v_exp_f32_e32 v26, v26
	v_sub_f32_e32 v27, v27, v94
	v_add_f32_e32 v41, v31, v41
	v_exp_f32_e32 v27, v27
	v_sub_f32_e32 v28, v28, v94
	v_add_f32_e32 v41, v32, v41
	v_exp_f32_e32 v28, v28
	v_sub_f32_e32 v29, v29, v94
	v_add_f32_e32 v41, v33, v41
	v_exp_f32_e32 v29, v29
	v_sub_f32_e32 v22, v22, v94
	v_add_f32_e32 v41, v26, v41
	v_exp_f32_e32 v22, v22
	v_sub_f32_e32 v23, v23, v94
	v_add_f32_e32 v41, v27, v41
	v_exp_f32_e32 v23, v23
	v_sub_f32_e32 v24, v24, v94
	v_add_f32_e32 v41, v28, v41
	v_exp_f32_e32 v24, v24
	v_sub_f32_e32 v25, v25, v94
	v_add_f32_e32 v41, v29, v41
	v_exp_f32_e32 v25, v25
	v_sub_f32_e32 v18, v18, v94
	v_add_f32_e32 v41, v22, v41
	v_exp_f32_e32 v18, v18
	v_sub_f32_e32 v19, v19, v94
	v_add_f32_e32 v41, v23, v41
	v_exp_f32_e32 v19, v19
	v_sub_f32_e32 v20, v20, v94
	v_add_f32_e32 v41, v24, v41
	v_exp_f32_e32 v20, v20
	v_sub_f32_e32 v21, v21, v94
	v_add_f32_e32 v41, v25, v41
	v_exp_f32_e32 v21, v21
	v_sub_f32_e32 v14, v14, v94
	v_add_f32_e32 v41, v18, v41
	v_exp_f32_e32 v14, v14
	v_sub_f32_e32 v15, v15, v94
	v_add_f32_e32 v41, v19, v41
	v_exp_f32_e32 v15, v15
	v_sub_f32_e32 v16, v16, v94
	v_add_f32_e32 v41, v20, v41
	v_exp_f32_e32 v16, v16
	v_sub_f32_e32 v17, v17, v94
	v_add_f32_e32 v41, v21, v41
	v_exp_f32_e32 v17, v17
	v_sub_f32_e32 v10, v10, v94
	v_add_f32_e32 v41, v14, v41
	v_exp_f32_e32 v10, v10
	v_sub_f32_e32 v11, v11, v94
	v_add_f32_e32 v41, v15, v41
	v_exp_f32_e32 v11, v11
	v_sub_f32_e32 v12, v12, v94
	v_add_f32_e32 v41, v16, v41
	v_exp_f32_e32 v12, v12
	v_sub_f32_e32 v13, v13, v94
	v_add_f32_e32 v41, v17, v41
	v_exp_f32_e32 v13, v13
	v_sub_f32_e32 v6, v6, v94
	v_add_f32_e32 v41, v10, v41
	v_exp_f32_e32 v6, v6
	v_sub_f32_e32 v7, v7, v94
	v_add_f32_e32 v41, v11, v41
	v_exp_f32_e32 v7, v7
	v_sub_f32_e32 v8, v8, v94
	v_add_f32_e32 v41, v12, v41
	v_exp_f32_e32 v8, v8
	v_sub_f32_e32 v9, v9, v94
	v_add_f32_e32 v41, v13, v41
	v_exp_f32_e32 v9, v9
	v_sub_f32_e32 v2, v2, v94
	v_add_f32_e32 v41, v6, v41
	v_exp_f32_e32 v52, v2
	v_sub_f32_e32 v3, v3, v94
	v_add_f32_e32 v41, v7, v41
	v_exp_f32_e32 v53, v3
	v_sub_f32_e32 v3, v4, v94
	v_add_f32_e32 v41, v8, v41
	v_exp_f32_e32 v54, v3
	v_sub_f32_e32 v3, v5, v94
	v_add_f32_e32 v41, v9, v41
	v_exp_f32_e32 v55, v3
	v_add_f32_e32 v2, v52, v41
	v_add_f32_e32 v2, v53, v2
	v_add_f32_e32 v2, v54, v2
	v_add_f32_e32 v2, v55, v2
	ds_bpermute_b32 v3, v114, v2
	v_cvt_pk_bf16_f32 v4, v86, v87
	v_cvt_pk_bf16_f32 v5, v88, v89
	ds_read_b128 v[84:87], v62 offset:8192
	ds_read_b128 v[88:91], v62 offset:16384
	s_waitcnt lgkmcnt(2)
	v_add_f32_e32 v2, v2, v3
	ds_bpermute_b32 v3, v115, v2
	v_cvt_pk_bf16_f32 v56, v47, v49
	v_cvt_pk_bf16_f32 v57, v58, v59
	v_cvt_pk_bf16_f32 v58, v60, v61
	v_cvt_pk_bf16_f32 v59, v77, v78
	s_waitcnt lgkmcnt(0)
; DI unsigned pk2(float lo, float hi) { const f32x2 v = {lo, hi}; const bf16x2_t b = __builtin_convertvector(v, bf16x2_t); return __builtin_bit_cast(unsigned, b); }
; DI f32x4 mfma16(bf16x8 a, bf16x8 b, f32x4 c) { return __builtin_amdgcn_mfma_f32_16x16x32_bf16(a, b, c, 0, 0, 0); }
; DI void unit_X(const Params& p, char* lds, int l, int chunk) {
;     ...
;         f32x4 o[4];
; #pragma unroll
;         for (int dt = 0; dt < 4; ++dt) o[dt] = (f32x4){0.f, 0.f, 0.f, 0.f};
; #pragma unroll
;         for (int ks = 0; ks < 8; ++ks) {
;             const f32x4 a = s[2 * ks], c = s[2 * ks + 1];
;             const u32x4 w = (u32x4){pk2(a[0], a[1]), pk2(a[2], a[3]), pk2(c[0], c[1]), pk2(c[2], c[3])};
;             const bf16x8 pb = __builtin_bit_cast(bf16x8, w);
; #pragma unroll
;             for (int dt = 0; dt < 4; ++dt) {
;                 const int row = 16 * dt + l15;
;                 const bf16x8 av = *(const bf16x8*)(vd + row * 512 + (((4 * ks + quad) ^ (row & 15)) << 4));
;                 o[dt] = mfma16(av, pb, o[dt]);
;             }
;         }
	v_add_f32_e32 v41, v2, v3
	v_cvt_pk_bf16_f32 v2, v95, v79
	v_cvt_pk_bf16_f32 v3, v80, v81
	ds_read_b128 v[80:83], v62
	ds_read_b128 v[92:95], v62 offset:24576
	s_waitcnt lgkmcnt(1)
	v_mfma_f32_16x16x32_bf16 v[80:83], v[80:83], v[2:5], 0
	v_cvt_pk_bf16_f32 v42, v42, v43
	v_cvt_pk_bf16_f32 v43, v44, v45
	v_cvt_pk_bf16_f32 v44, v46, v48
	v_mfma_f32_16x16x32_bf16 v[84:87], v[84:87], v[2:5], 0
	ds_read_b128 v[46:49], v64
	v_cvt_pk_bf16_f32 v45, v50, v51
	v_cvt_pk_bf16_f32 v30, v30, v31
	v_mfma_f32_16x16x32_bf16 v[88:91], v[88:91], v[2:5], 0
	v_cvt_pk_bf16_f32 v31, v32, v33
	v_cvt_pk_bf16_f32 v32, v26, v27
	v_cvt_pk_bf16_f32 v33, v28, v29
	s_waitcnt lgkmcnt(1)
	v_mfma_f32_16x16x32_bf16 v[2:5], v[92:95], v[2:5], 0
	ds_read_b128 v[92:95], v63
	ds_read_b128 v[26:29], v66
	v_cvt_pk_bf16_f32 v22, v22, v23
	s_waitcnt lgkmcnt(1)
	v_mfma_f32_16x16x32_bf16 v[78:81], v[92:95], v[56:59], v[80:83]
	ds_read_b128 v[92:95], v63 offset:8192
	v_cvt_pk_bf16_f32 v23, v24, v25
	v_cvt_pk_bf16_f32 v24, v18, v19
	v_mfma_f32_16x16x32_bf16 v[46:49], v[46:49], v[42:45], v[78:81]
	v_cvt_pk_bf16_f32 v25, v20, v21
	ds_read_b128 v[18:21], v67
	v_cvt_pk_bf16_f32 v14, v14, v15
	s_nop 0
	ds_read_b128 v[78:81], v64 offset:24576
	s_waitcnt lgkmcnt(2)
	v_mfma_f32_16x16x32_bf16 v[82:85], v[92:95], v[56:59], v[84:87]
	ds_read_b128 v[92:95], v63 offset:16384
	ds_read_b128 v[60:63], v63 offset:24576
	v_cvt_pk_bf16_f32 v15, v16, v17
	s_waitcnt lgkmcnt(1)
	v_mfma_f32_16x16x32_bf16 v[86:89], v[92:95], v[56:59], v[88:91]
	v_cvt_pk_bf16_f32 v16, v10, v11
	v_cvt_pk_bf16_f32 v17, v12, v13
	ds_read_b128 v[10:13], v68
	s_waitcnt lgkmcnt(1)
	v_mfma_f32_16x16x32_bf16 v[2:5], v[60:63], v[56:59], v[2:5]
	ds_read_b128 v[56:59], v64 offset:8192
	ds_read_b128 v[60:63], v64 offset:16384
	s_waitcnt lgkmcnt(1)
	v_mfma_f32_16x16x32_bf16 v[56:59], v[56:59], v[42:45], v[82:85]
	s_waitcnt lgkmcnt(0)
	v_mfma_f32_16x16x32_bf16 v[60:63], v[60:63], v[42:45], v[86:89]
	v_mfma_f32_16x16x32_bf16 v[2:5], v[78:81], v[42:45], v[2:5]
	v_cvt_pk_bf16_f32 v44, v34, v35
	v_cvt_pk_bf16_f32 v45, v36, v37
	ds_read_b128 v[34:37], v65
	v_cvt_pk_bf16_f32 v42, v0, v38
	v_cvt_pk_bf16_f32 v43, v39, v40
	v_div_scale_f32 v0, s[0:1], v41, v41, 1.0
	s_waitcnt lgkmcnt(0)
	v_mfma_f32_16x16x32_bf16 v[34:37], v[34:37], v[42:45], v[46:49]
	s_nop 2
	ds_read_b128 v[46:49], v65 offset:8192
	v_mfma_f32_16x16x32_bf16 v[26:29], v[26:29], v[30:33], v[34:37]
	s_nop 2
	ds_read_b128 v[34:37], v66 offset:8192
	s_waitcnt lgkmcnt(1)
	v_mfma_f32_16x16x32_bf16 v[46:49], v[46:49], v[42:45], v[56:59]
	s_nop 2
	ds_read_b128 v[56:59], v65 offset:16384
	s_waitcnt lgkmcnt(1)
	v_mfma_f32_16x16x32_bf16 v[34:37], v[34:37], v[30:33], v[46:49]
	s_nop 2
	ds_read_b128 v[46:49], v66 offset:24576
	s_waitcnt lgkmcnt(1)
	v_mfma_f32_16x16x32_bf16 v[56:59], v[56:59], v[42:45], v[60:63]
	s_nop 2
	ds_read_b128 v[60:63], v65 offset:24576
	v_mfma_f32_16x16x32_bf16 v[18:21], v[18:21], v[22:25], v[26:29]
	s_nop 2
	ds_read_b128 v[26:29], v67 offset:8192
	s_waitcnt lgkmcnt(1)
	v_mfma_f32_16x16x32_bf16 v[2:5], v[60:63], v[42:45], v[2:5]
	ds_read_b128 v[42:45], v66 offset:16384
	v_mfma_f32_16x16x32_bf16 v[2:5], v[46:49], v[30:33], v[2:5]
	s_waitcnt lgkmcnt(1)
	v_mfma_f32_16x16x32_bf16 v[26:29], v[26:29], v[22:25], v[34:37]
	s_nop 2
	ds_read_b128 v[34:37], v67 offset:24576
	s_waitcnt lgkmcnt(1)
	v_mfma_f32_16x16x32_bf16 v[42:45], v[42:45], v[30:33], v[56:59]
	ds_read_b128 v[30:33], v67 offset:16384
	v_mfma_f32_16x16x32_bf16 v[10:13], v[10:13], v[14:17], v[18:21]
	s_nop 2
	ds_read_b128 v[18:21], v68 offset:8192
	s_waitcnt lgkmcnt(1)
	v_mfma_f32_16x16x32_bf16 v[30:33], v[30:33], v[22:25], v[42:45]
	v_mfma_f32_16x16x32_bf16 v[2:5], v[34:37], v[22:25], v[2:5]
	ds_read_b128 v[22:25], v68 offset:16384
	s_waitcnt lgkmcnt(1)
; DI unsigned pk2(float lo, float hi) { const f32x2 v = {lo, hi}; const bf16x2_t b = __builtin_convertvector(v, bf16x2_t); return __builtin_bit_cast(unsigned, b); }
; DI float bf2f(unsigned b) { return __uint_as_float(b << 16); }
; DI f32x4 mfma16(bf16x8 a, bf16x8 b, f32x4 c) { return __builtin_amdgcn_mfma_f32_16x16x32_bf16(a, b, c, 0, 0, 0); }
; DI size_t y_off(int tok, int col) { return ((size_t)(((tok >> 6) * 32 + (col >> 5)) * 64 + (tok & 63))) * 32 + (col & 31); }
; DI void unit_X(const Params& p, char* lds, int l, int chunk) {
;     ...
;         const float inv = 1.f / sum;
;         f32x4 o[4];
; #pragma unroll
;         for (int dt = 0; dt < 4; ++dt) o[dt] = (f32x4){0.f, 0.f, 0.f, 0.f};
; #pragma unroll
;         for (int ks = 0; ks < 8; ++ks) {
;             const f32x4 a = s[2 * ks], c = s[2 * ks + 1];
;             const u32x4 w = (u32x4){pk2(a[0], a[1]), pk2(a[2], a[3]), pk2(c[0], c[1]), pk2(c[2], c[3])};
;             const bf16x8 pb = __builtin_bit_cast(bf16x8, w);
; #pragma unroll
;             for (int dt = 0; dt < 4; ++dt) {
;                 const int row = 16 * dt + l15;
;                 const bf16x8 av = *(const bf16x8*)(vd + row * 512 + (((4 * ks + quad) ^ (row & 15)) << 4));
;                 o[dt] = mfma16(av, pb, o[dt]);
;             }
;         }
; #pragma unroll
;         for (int dt = 0; dt < 4; ++dt) {
;             const int d = 16 * dt + 4 * quad;
;             const u32x2 gv = *(const u32x2*)(gx + (size_t)tok * 256 + 64 * h + d);
;             const float o0 = o[dt][0] * inv * bf2f(gv[0] & 0xffffu), o1 = o[dt][1] * inv * bf2f(gv[0] >> 16);
;             const float o2 = o[dt][2] * inv * bf2f(gv[1] & 0xffffu), o3 = o[dt][3] * inv * bf2f(gv[1] >> 16);
;             *(u32x2*)(yo + y_off(chunk * 128 + tok, 768 + h * 64 + d)) = (u32x2){pk2(o0, o1), pk2(o2, o3)};
;         }
	v_mfma_f32_16x16x32_bf16 v[18:21], v[18:21], v[14:17], v[26:29]
	s_nop 2
	ds_read_b128 v[26:29], v68 offset:24576
	s_waitcnt lgkmcnt(0)
	v_mfma_f32_16x16x32_bf16 v[2:5], v[26:29], v[14:17], v[2:5]
	v_cvt_pk_bf16_f32 v26, v6, v7
	v_cvt_pk_bf16_f32 v27, v8, v9
	ds_read_b128 v[6:9], v69
	v_cvt_pk_bf16_f32 v28, v52, v53
	v_cvt_pk_bf16_f32 v29, v54, v55
	v_mfma_f32_16x16x32_bf16 v[22:25], v[22:25], v[14:17], v[30:33]
	s_waitcnt lgkmcnt(0)
	v_mfma_f32_16x16x32_bf16 v[14:17], v[6:9], v[26:29], v[10:13]
	ds_read_b128 v[6:9], v69 offset:8192
	s_waitcnt lgkmcnt(0)
	v_mfma_f32_16x16x32_bf16 v[10:13], v[6:9], v[26:29], v[18:21]
	ds_read_b128 v[6:9], v69 offset:16384
	s_nop 1
	ds_read_b128 v[18:21], v69 offset:24576
	s_waitcnt lgkmcnt(0)
	v_mfma_f32_16x16x32_bf16 v[2:5], v[18:21], v[26:29], v[2:5]
	v_rcp_f32_e32 v18, v0
	s_nop 0
	v_fma_f32 v19, -v0, v18, 1.0
	v_fmac_f32_e32 v18, v19, v18
	v_div_scale_f32 v19, vcc, 1.0, v41, 1.0
	v_mul_f32_e32 v20, v19, v18
	v_fma_f32 v21, -v0, v20, v19
	v_fmac_f32_e32 v20, v21, v18
	v_fma_f32 v0, -v0, v20, v19
	v_div_fmas_f32 v0, v0, v18, v20
	v_div_fixup_f32 v0, v0, v41, 1.0
	v_pk_mul_f32 v[14:15], v[14:15], v[0:1] op_sel_hi:[1,0]
	v_pk_mul_f32 v[16:17], v[16:17], v[0:1] op_sel_hi:[1,0]
	v_pk_mul_f32 v[10:11], v[10:11], v[0:1] op_sel_hi:[1,0]
	v_pk_mul_f32 v[12:13], v[12:13], v[0:1] op_sel_hi:[1,0]
	v_mfma_f32_16x16x32_bf16 v[6:9], v[6:9], v[26:29], v[22:25]
	v_mul_f32_e64 v2, v2, v0
	v_mul_f32_e64 v3, v3, v0
	v_pk_mul_f32 v[4:5], v[4:5], v[0:1] op_sel_hi:[1,0]
	s_waitcnt vmcnt(0)
	v_mov_b32_e32 v18, v228
	v_mov_b32_e32 v19, v229
	v_lshlrev_b32_e32 v20, 16, v18
	v_and_b32_e32 v21, 0xffff0000, v18
	v_lshlrev_b32_e32 v18, 16, v19
	v_and_b32_e32 v19, 0xffff0000, v19
	v_pk_mul_f32 v[14:15], v[14:15], v[20:21]
	v_pk_mul_f32 v[16:17], v[16:17], v[18:19]
	v_cvt_pk_bf16_f32 v14, v14, v15
	v_cvt_pk_bf16_f32 v15, v16, v17
	v_or_b32_e32 v16, 0x780, v76
	v_ashrrev_i32_e32 v17, 31, v16
	v_lshlrev_b64 v[16:17], 6, v[16:17]
	v_lshl_add_u64 v[16:17], s[54:55], 0, v[16:17]
	v_lshl_add_u64 v[16:17], v[16:17], 0, v[72:73]
	global_store_dwordx2 v[16:17], v[14:15], off
	v_pk_mul_f32 v[6:7], v[6:7], v[0:1] op_sel_hi:[1,0]
	v_pk_mul_f32 v[8:9], v[8:9], v[0:1] op_sel_hi:[1,0]
	s_nop 1
	v_mov_b32_e32 v14, v230
	v_mov_b32_e32 v15, v231
	v_lshlrev_b32_e32 v18, 16, v14
	v_and_b32_e32 v19, 0xffff0000, v14
	v_lshlrev_b32_e32 v14, 16, v15
	v_and_b32_e32 v15, 0xffff0000, v15
	v_pk_mul_f32 v[10:11], v[10:11], v[18:19]
	v_pk_mul_f32 v[12:13], v[12:13], v[14:15]
	v_cvt_pk_bf16_f32 v10, v10, v11
	v_cvt_pk_bf16_f32 v11, v12, v13
	global_store_dwordx2 v[16:17], v[10:11], off offset:32
	s_nop 1
	v_mov_b32_e32 v10, v232
	v_mov_b32_e32 v11, v233
	v_lshlrev_b32_e32 v12, 16, v10
	v_and_b32_e32 v13, 0xffff0000, v10
	v_lshlrev_b32_e32 v10, 16, v11
	v_and_b32_e32 v11, 0xffff0000, v11
	v_pk_mul_f32 v[6:7], v[6:7], v[12:13]
	v_pk_mul_f32 v[8:9], v[8:9], v[10:11]
	v_cvt_pk_bf16_f32 v6, v6, v7
	v_cvt_pk_bf16_f32 v7, v8, v9
	v_or_b32_e32 v8, 0x7c0, v76
	v_ashrrev_i32_e32 v9, 31, v8
	v_lshlrev_b64 v[8:9], 6, v[8:9]
	v_lshl_add_u64 v[8:9], s[54:55], 0, v[8:9]
	v_lshl_add_u64 v[10:11], v[8:9], 0, v[72:73]
	global_store_dwordx2 v[10:11], v[6:7], off
	s_nop 1
	v_mov_b32_e32 v6, v234
	v_mov_b32_e32 v7, v235
	v_lshlrev_b32_e32 v10, 16, v6
	v_and_b32_e32 v11, 0xffff0000, v6
	v_lshlrev_b32_e32 v6, 16, v7
	v_and_b32_e32 v7, 0xffff0000, v7
	v_pk_mul_f32 v[2:3], v[2:3], v[10:11]
	v_pk_mul_f32 v[4:5], v[4:5], v[6:7]
	v_cvt_pk_bf16_f32 v2, v2, v3
	v_cvt_pk_bf16_f32 v3, v4, v5
	v_lshl_add_u64 v[4:5], v[8:9], 0, v[74:75]
	global_store_dwordx2 v[4:5], v[2:3], off

; __global__ void __launch_bounds__(NTHR) mega_fwd(Params p) {
;     extern __shared__ __attribute__((aligned(16))) char lds[];
;     cg::grid_group grid = cg::this_grid();
;     const int nb = gridDim.x, bid = blockIdx.x;
;     if (bid == 0 && threadIdx.x < 256) __hip_atomic_store(WS_PTR(unsigned, OFF_HL) + threadIdx.x, 0u, __ATOMIC_RELAXED, __HIP_MEMORY_SCOPE_AGENT);
;     prep_phase(p, lds);
;     unsigned* bar = WS_PTR(unsigned, OFF_HL);
;     for (int ph = 0; ph < 4; ++ph) {
;         if (ph == 0) grid.sync(); else fast_grid_barrier(bar, (unsigned)ph * (unsigned)nb);
;         const int l = ph >> 1;
;         if ((ph & 1) == 0) {
;             const int nkv = (l == 0) ? 256 : 0, nunits = 256 + nkv + 1024 + 256 + 256;
;             for (int u = bid; u < nunits; u += nb) {
;                 int v = u;
;                 if (v < 256) { unit_B1(p, lds, l, v); continue; }
;                 v -= 256;
;                 if (v < nkv) { unit_KV(p, lds, v >> 7, (v >> 2) & 31, v & 3); continue; }
;                 v -= nkv;
;                 if (v < 1024) { unit_A(p, lds, l, v & 255, v >> 8); continue; }
;                 v -= 1024;
;                 const int s = v & 255, xcd = s & 7, i = s >> 3;
;                 if (v < 256) unit_X(p, lds, l, xcd * 32 + i);
;                 else unit_S5(p, lds, l, xcd * 2 + (i >> 4), i & 15);
;             }
;         } else {
;             for (int u = bid; u < 512; u += 2 * nb) {
;                 const int ub = u + nb;
;                 unit_O(p, lds, l, u, ub < 512 ? 2 : 1, ub);
;                 if (ub < 512) unit_O(p, lds, l, ub, 0, 0);
;             }
;         }
;     }
; }
	.amdhsa_kernel _Z8mega_fwd6Params
		.amdhsa_group_segment_fixed_size 0
		.amdhsa_private_segment_fixed_size 0
		.amdhsa_kernarg_size 448
		.amdhsa_user_sgpr_count 2
		.amdhsa_user_sgpr_dispatch_ptr 0
		.amdhsa_user_sgpr_queue_ptr 0
		.amdhsa_user_sgpr_kernarg_segment_ptr 1
		.amdhsa_user_sgpr_dispatch_id 0
		.amdhsa_user_sgpr_kernarg_preload_length 0
		.amdhsa_user_sgpr_kernarg_preload_offset 0
		.amdhsa_user_sgpr_private_segment_size 0
		.amdhsa_uses_dynamic_stack 0
		.amdhsa_enable_private_segment 0
		.amdhsa_system_sgpr_workgroup_id_x 1
		.amdhsa_system_sgpr_workgroup_id_y 0
		.amdhsa_system_sgpr_workgroup_id_z 0
		.amdhsa_system_sgpr_workgroup_info 0
		.amdhsa_system_vgpr_workitem_id 2
		.amdhsa_next_free_vgpr 246
		.amdhsa_next_free_sgpr 98
		.amdhsa_accum_offset 248
		.amdhsa_reserve_vcc 1
		.amdhsa_float_round_mode_32 0
		.amdhsa_float_round_mode_16_64 0
		.amdhsa_float_denorm_mode_32 3
		.amdhsa_float_denorm_mode_16_64 3
		.amdhsa_dx10_clamp 1
		.amdhsa_ieee_mode 1
		.amdhsa_fp16_overflow 0
		.amdhsa_tg_split 0
		.amdhsa_exception_fp_ieee_invalid_op 0
		.amdhsa_exception_fp_denorm_src 0
		.amdhsa_exception_fp_ieee_div_zero 0
		.amdhsa_exception_fp_ieee_overflow 0
		.amdhsa_exception_fp_ieee_underflow 0
		.amdhsa_exception_fp_ieee_inexact 0
		.amdhsa_exception_int_div_zero 0
	.end_amdhsa_kernel

; __global__ void __launch_bounds__(NTHR) mega_fwd(Params p) {
;     extern __shared__ __attribute__((aligned(16))) char lds[];
;     cg::grid_group grid = cg::this_grid();
;     const int nb = gridDim.x, bid = blockIdx.x;
;     if (bid == 0 && threadIdx.x < 256) __hip_atomic_store(WS_PTR(unsigned, OFF_HL) + threadIdx.x, 0u, __ATOMIC_RELAXED, __HIP_MEMORY_SCOPE_AGENT);
;     prep_phase(p, lds);
;     unsigned* bar = WS_PTR(unsigned, OFF_HL);
;     for (int ph = 0; ph < 4; ++ph) {
;         if (ph == 0) grid.sync(); else fast_grid_barrier(bar, (unsigned)ph * (unsigned)nb);
;         const int l = ph >> 1;
;         if ((ph & 1) == 0) {
;             const int nkv = (l == 0) ? 256 : 0, nunits = 256 + nkv + 1024 + 256 + 256;
;             for (int u = bid; u < nunits; u += nb) {
;                 int v = u;
;                 if (v < 256) { unit_B1(p, lds, l, v); continue; }
;                 v -= 256;
;                 if (v < nkv) { unit_KV(p, lds, v >> 7, (v >> 2) & 31, v & 3); continue; }
;                 v -= nkv;
;                 if (v < 1024) { unit_A(p, lds, l, v & 255, v >> 8); continue; }
;                 v -= 1024;
;                 const int s = v & 255, xcd = s & 7, i = s >> 3;
;                 if (v < 256) unit_X(p, lds, l, xcd * 32 + i);
;                 else unit_S5(p, lds, l, xcd * 2 + (i >> 4), i & 15);
;             }
;         } else {
;             for (int u = bid; u < 512; u += 2 * nb) {
;                 const int ub = u + nb;
;                 unit_O(p, lds, l, u, ub < 512 ? 2 : 1, ub);
;                 if (ub < 512) unit_O(p, lds, l, ub, 0, 0);
;             }
;         }
;     }
; }
amdhsa.kernels:
  - .agpr_count:     0
    .args:
      - .offset:         0
        .size:           192
        .value_kind:     by_value
      - .offset:         192
        .size:           4
        .value_kind:     hidden_block_count_x
      - .offset:         196
        .size:           4
        .value_kind:     hidden_block_count_y
      - .offset:         200
        .size:           4
        .value_kind:     hidden_block_count_z
      - .offset:         204
        .size:           2
        .value_kind:     hidden_group_size_x
      - .offset:         206
        .size:           2
        .value_kind:     hidden_group_size_y
      - .offset:         208
        .size:           2
        .value_kind:     hidden_group_size_z
      - .offset:         210
        .size:           2
        .value_kind:     hidden_remainder_x
      - .offset:         212
        .size:           2
        .value_kind:     hidden_remainder_y
      - .offset:         214
        .size:           2
        .value_kind:     hidden_remainder_z
      - .offset:         232
        .size:           8
        .value_kind:     hidden_global_offset_x
      - .offset:         240
        .size:           8
        .value_kind:     hidden_global_offset_y
      - .offset:         248
        .size:           8
        .value_kind:     hidden_global_offset_z
      - .offset:         256
        .size:           2
        .value_kind:     hidden_grid_dims
      - .offset:         280
        .size:           8
        .value_kind:     hidden_multigrid_sync_arg
      - .offset:         312
        .size:           4
        .value_kind:     hidden_dynamic_lds_size
    .group_segment_fixed_size: 0
    .kernarg_segment_align: 8
    .kernarg_segment_size: 448
    .language:       OpenCL C
    .language_version:
      - 2
      - 0
    .max_flat_workgroup_size: 512
    .name:           _Z8mega_fwd6Params
    .private_segment_fixed_size: 0
    .sgpr_count:     104
    .sgpr_spill_count: 182
    .symbol:         _Z8mega_fwd6Params.kd
    .uniform_work_group_size: 1
    .uses_dynamic_stack: false
    .vgpr_count:     246
    .vgpr_spill_count: 0
    .wavefront_size: 64
